# gate sigmoids (in-proj gates epilogue, PLE gate) use clamped v_rcp_f32 + one Newton step instead of the IEEE division chain; gates epilogue hand-written with 32-bit addressing
# speedup vs baseline: 1.7116x; 1.0136x over previous
; #define ZERO_ACC(a) ZERO_ACCM(a, 2)
; #define EPI_BEGIN(accv) EPI_BEGINM(accv, 2)
; DI float sigmoidf_(float v) { return 1.f / (1.f + __expf(-v)); }
; DI void phase_ple(const Params& p, int L, char* smem) {
;     ...
;     f32x16 gt[2][2]; ZERO_ACC(gt)
;     gemm_core<true>(p.xb, D, p.wt_pg, D, D, m0, n0, gt, smem);
;     EPI_BEGIN(gt) gt[mt][nt][i] = sigmoidf_(v * rstd_s[rl]); EPI_END
.LBB0_11:
	s_or_b64 exec, exec, s[2:3]
	s_waitcnt lgkmcnt(0)
	s_barrier
	ds_read_b128 v[68:71], v158 offset:55296
	ds_read_b128 v[64:67], v158 offset:55328
	v_readlane_b32 s16, v253, 48
	v_mov_b32_e32 v105, v189
	v_readlane_b32 s30, v253, 62
	s_waitcnt lgkmcnt(1)
	v_mul_f32_e32 v48, v48, v68
	v_mul_f32_e32 v48, 0xbfb8aa3b, v48
	v_exp_f32_e32 v48, v48
	v_mul_f32_e32 v32, v32, v68
	v_mul_f32_e32 v32, 0xbfb8aa3b, v32
	v_exp_f32_e32 v32, v32
	v_add_f32_e32 v48, 1.0, v48
	s_waitcnt vmcnt(3)
	v_min_f32_e32 v72, 0x7f7fffff, v48
	v_rcp_f32_e32 v73, v72
	v_add_f32_e32 v32, 1.0, v32
	v_readlane_b32 s31, v253, 63
	s_mov_b32 s7, 0xfffffc0
	v_fma_f32 v74, -v72, v73, 1.0
	v_fmac_f32_e32 v73, v74, v73
	s_waitcnt vmcnt(2)
	v_mov_b32_e32 v110, v73
	v_mul_f32_e32 v48, v49, v69
	v_mul_f32_e32 v48, 0xbfb8aa3b, v48
	v_exp_f32_e32 v48, v48
	s_movk_i32 s6, 0x90
	v_readlane_b32 s52, v253, 32
	v_readlane_b32 s64, v253, 44
	v_add_f32_e32 v48, 1.0, v48
	v_min_f32_e32 v49, 0x7f7fffff, v48
	v_rcp_f32_e32 v72, v49
	v_readlane_b32 s65, v253, 45
	v_readlane_b32 s28, v253, 60
	v_readlane_b32 s29, v253, 61
	v_fma_f32 v73, -v49, v72, 1.0
	v_fmac_f32_e32 v72, v73, v72
	v_mov_b32_e32 v114, v72
	v_mul_f32_e32 v48, v50, v70
	v_mul_f32_e32 v48, 0xbfb8aa3b, v48
	v_exp_f32_e32 v48, v48
	v_readlane_b32 s17, v253, 49
	v_readlane_b32 s18, v253, 50
	v_readlane_b32 s19, v253, 51
	v_add_f32_e32 v48, 1.0, v48
	v_min_f32_e32 v49, 0x7f7fffff, v48
	v_rcp_f32_e32 v50, v49
	v_readlane_b32 s20, v253, 52
	v_readlane_b32 s21, v253, 53
	v_readlane_b32 s22, v253, 54
	v_fma_f32 v72, -v49, v50, 1.0
	v_fmac_f32_e32 v50, v72, v50
	v_mov_b32_e32 v118, v50
	v_mul_f32_e32 v48, v51, v71
	v_mul_f32_e32 v48, 0xbfb8aa3b, v48
	v_exp_f32_e32 v48, v48
	v_readlane_b32 s23, v253, 55
	v_readlane_b32 s24, v253, 56
	v_readlane_b32 s25, v253, 57
	v_add_f32_e32 v48, 1.0, v48
	v_min_f32_e32 v49, 0x7f7fffff, v48
	v_rcp_f32_e32 v50, v49
	v_readlane_b32 s26, v253, 58
	v_readlane_b32 s27, v253, 59
	v_readlane_b32 s53, v253, 33
	v_fma_f32 v51, -v49, v50, 1.0
	v_fmac_f32_e32 v50, v51, v50
	v_mov_b32_e32 v117, v50
	s_waitcnt lgkmcnt(0)
	v_mul_f32_e32 v48, v52, v64
	v_mul_f32_e32 v48, 0xbfb8aa3b, v48
	v_exp_f32_e32 v48, v48
	v_readlane_b32 s54, v253, 34
	v_readlane_b32 s55, v253, 35
	v_readlane_b32 s56, v253, 36
	v_add_f32_e32 v48, 1.0, v48
	v_min_f32_e32 v49, 0x7f7fffff, v48
	v_rcp_f32_e32 v50, v49
	v_readlane_b32 s57, v253, 37
	v_readlane_b32 s58, v253, 38
	v_readlane_b32 s59, v253, 39
	v_fma_f32 v51, -v49, v50, 1.0
	v_fmac_f32_e32 v50, v51, v50
	v_mov_b32_e32 v119, v50
	v_mul_f32_e32 v48, v53, v65
	v_mul_f32_e32 v48, 0xbfb8aa3b, v48
	v_exp_f32_e32 v48, v48
	v_readlane_b32 s60, v253, 40
	v_readlane_b32 s61, v253, 41
	v_readlane_b32 s62, v253, 42
	v_add_f32_e32 v48, 1.0, v48
	v_min_f32_e32 v49, 0x7f7fffff, v48
	v_rcp_f32_e32 v50, v49
	v_readlane_b32 s63, v253, 43
	v_readlane_b32 s66, v253, 46
	v_readlane_b32 s67, v253, 47
	v_fma_f32 v51, -v49, v50, 1.0
	v_fmac_f32_e32 v50, v51, v50
	v_mov_b32_e32 v123, v50
	v_mul_f32_e32 v48, v54, v66
	v_mul_f32_e32 v48, 0xbfb8aa3b, v48
	v_exp_f32_e32 v48, v48
	s_nop 0
	v_add_f32_e32 v48, 1.0, v48
	v_min_f32_e32 v49, 0x7f7fffff, v48
	v_rcp_f32_e32 v50, v49
	s_nop 0
	v_fma_f32 v51, -v49, v50, 1.0
	v_fmac_f32_e32 v50, v51, v50
	v_mov_b32_e32 v125, v50
	v_mul_f32_e32 v48, v55, v67
	v_mul_f32_e32 v48, 0xbfb8aa3b, v48
	v_exp_f32_e32 v48, v48
	s_nop 0
	v_add_f32_e32 v48, 1.0, v48
	v_min_f32_e32 v49, 0x7f7fffff, v48
	v_rcp_f32_e32 v50, v49
	s_nop 0
	v_fma_f32 v51, -v49, v50, 1.0
	v_fmac_f32_e32 v50, v51, v50
	v_mov_b32_e32 v128, v50
	ds_read_b128 v[48:51], v158 offset:55360
	s_waitcnt lgkmcnt(0)
	v_mul_f32_e32 v52, v56, v48
	v_mul_f32_e32 v52, 0xbfb8aa3b, v52
	v_exp_f32_e32 v52, v52
	s_nop 0
	v_add_f32_e32 v52, 1.0, v52
	v_min_f32_e32 v53, 0x7f7fffff, v52
	v_rcp_f32_e32 v54, v53
	s_nop 0
	v_fma_f32 v55, -v53, v54, 1.0
	v_fmac_f32_e32 v54, v55, v54
	v_mov_b32_e32 v132, v54
	v_mul_f32_e32 v52, v57, v49
	v_mul_f32_e32 v52, 0xbfb8aa3b, v52
	v_exp_f32_e32 v52, v52
	s_nop 0
	v_add_f32_e32 v52, 1.0, v52
	v_min_f32_e32 v53, 0x7f7fffff, v52
	v_rcp_f32_e32 v54, v53
	s_nop 0
	v_fma_f32 v55, -v53, v54, 1.0
	v_fmac_f32_e32 v54, v55, v54
	v_mov_b32_e32 v133, v54
	v_mul_f32_e32 v52, v58, v50
	v_mul_f32_e32 v52, 0xbfb8aa3b, v52
	v_exp_f32_e32 v52, v52
	s_nop 0
	v_add_f32_e32 v52, 1.0, v52
	v_min_f32_e32 v53, 0x7f7fffff, v52
	v_rcp_f32_e32 v54, v53
	s_nop 0
	v_fma_f32 v55, -v53, v54, 1.0
	v_fmac_f32_e32 v54, v55, v54
	v_mov_b32_e32 v134, v54
	v_mul_f32_e32 v52, v59, v51
	v_mul_f32_e32 v52, 0xbfb8aa3b, v52
	v_exp_f32_e32 v52, v52
	s_nop 0
	v_add_f32_e32 v52, 1.0, v52
	v_min_f32_e32 v53, 0x7f7fffff, v52
	v_rcp_f32_e32 v54, v53
	s_nop 0
	v_fma_f32 v55, -v53, v54, 1.0
	v_fmac_f32_e32 v54, v55, v54
	v_mov_b32_e32 v135, v54
	ds_read_b128 v[52:55], v158 offset:55392
	s_waitcnt lgkmcnt(0)
; #define ZERO_ACC(a) ZERO_ACCM(a, 2)
; #define EPI_BEGIN(accv) EPI_BEGINM(accv, 2)
; DI float sigmoidf_(float v) { return 1.f / (1.f + __expf(-v)); }
; DI void phase_ple(const Params& p, int L, char* smem) {
;     ...
;     f32x16 gt[2][2]; ZERO_ACC(gt)
;     gemm_core<true>(p.xb, D, p.wt_pg, D, D, m0, n0, gt, smem);
;     EPI_BEGIN(gt) gt[mt][nt][i] = sigmoidf_(v * rstd_s[rl]); EPI_END
	v_mul_f32_e32 v56, v60, v52
	v_mul_f32_e32 v56, 0xbfb8aa3b, v56
	v_exp_f32_e32 v56, v56
	s_nop 0
	v_add_f32_e32 v56, 1.0, v56
	v_min_f32_e32 v57, 0x7f7fffff, v56
	v_rcp_f32_e32 v58, v57
	s_nop 0
	v_fma_f32 v59, -v57, v58, 1.0
	v_fmac_f32_e32 v58, v59, v58
	v_mov_b32_e32 v161, v58
	v_mul_f32_e32 v56, v61, v53
	v_mul_f32_e32 v56, 0xbfb8aa3b, v56
	v_exp_f32_e32 v56, v56
	s_nop 0
	v_add_f32_e32 v56, 1.0, v56
	v_min_f32_e32 v57, 0x7f7fffff, v56
	v_rcp_f32_e32 v58, v57
	s_nop 0
	v_fma_f32 v59, -v57, v58, 1.0
	v_fmac_f32_e32 v58, v59, v58
	v_mov_b32_e32 v163, v58
	v_mul_f32_e32 v56, v62, v54
	v_mul_f32_e32 v56, 0xbfb8aa3b, v56
	v_exp_f32_e32 v56, v56
	s_nop 0
	v_add_f32_e32 v56, 1.0, v56
	v_min_f32_e32 v57, 0x7f7fffff, v56
	v_rcp_f32_e32 v58, v57
	s_nop 0
	v_fma_f32 v59, -v57, v58, 1.0
	v_fmac_f32_e32 v58, v59, v58
	v_mov_b32_e32 v165, v58
	v_mul_f32_e32 v56, v63, v55
	v_mul_f32_e32 v56, 0xbfb8aa3b, v56
	v_exp_f32_e32 v56, v56
	s_nop 0
	v_add_f32_e32 v56, 1.0, v56
	v_min_f32_e32 v57, 0x7f7fffff, v56
	v_rcp_f32_e32 v58, v57
	s_nop 0
	v_fma_f32 v59, -v57, v58, 1.0
	v_fmac_f32_e32 v58, v59, v58
	v_mov_b32_e32 v170, v58
	v_min_f32_e32 v56, 0x7f7fffff, v32
	v_rcp_f32_e32 v57, v56
	s_nop 0
	v_fma_f32 v58, -v56, v57, 1.0
	v_fmac_f32_e32 v57, v58, v57
	v_mov_b32_e32 v171, v57
	v_mul_f32_e32 v32, v33, v69
	v_mul_f32_e32 v32, 0xbfb8aa3b, v32
	v_exp_f32_e32 v32, v32
	s_nop 0
	v_add_f32_e32 v32, 1.0, v32
	v_min_f32_e32 v33, 0x7f7fffff, v32
	v_rcp_f32_e32 v56, v33
	s_nop 0
	v_fma_f32 v57, -v33, v56, 1.0
	v_fmac_f32_e32 v56, v57, v56
	v_mov_b32_e32 v172, v56
	v_mul_f32_e32 v32, v34, v70
	v_mul_f32_e32 v32, 0xbfb8aa3b, v32
	v_exp_f32_e32 v32, v32
	s_nop 0
	v_add_f32_e32 v32, 1.0, v32
	v_min_f32_e32 v33, 0x7f7fffff, v32
	v_rcp_f32_e32 v34, v33
	s_nop 0
	v_fma_f32 v56, -v33, v34, 1.0
	v_fmac_f32_e32 v34, v56, v34
	v_mov_b32_e32 v173, v34
	v_mul_f32_e32 v32, v35, v71
	v_mul_f32_e32 v32, 0xbfb8aa3b, v32
	v_exp_f32_e32 v32, v32
	s_nop 0
	v_add_f32_e32 v32, 1.0, v32
	v_min_f32_e32 v33, 0x7f7fffff, v32
	v_rcp_f32_e32 v34, v33
	s_nop 0
	v_fma_f32 v35, -v33, v34, 1.0
	v_fmac_f32_e32 v34, v35, v34
	v_mov_b32_e32 v142, v34
	v_mul_f32_e32 v32, v36, v64
	v_mul_f32_e32 v32, 0xbfb8aa3b, v32
	v_exp_f32_e32 v32, v32
	s_nop 0
	v_add_f32_e32 v32, 1.0, v32
	v_min_f32_e32 v33, 0x7f7fffff, v32
	v_rcp_f32_e32 v34, v33
	s_nop 0
	v_fma_f32 v35, -v33, v34, 1.0
	v_fmac_f32_e32 v34, v35, v34
	v_mov_b32_e32 v148, v34
	v_mul_f32_e32 v32, v37, v65
	v_mul_f32_e32 v32, 0xbfb8aa3b, v32
	v_exp_f32_e32 v32, v32
	s_nop 0
	v_add_f32_e32 v32, 1.0, v32
	v_min_f32_e32 v33, 0x7f7fffff, v32
	v_rcp_f32_e32 v34, v33
	s_nop 0
	v_fma_f32 v35, -v33, v34, 1.0
	v_fmac_f32_e32 v34, v35, v34
	v_mov_b32_e32 v153, v34
	v_mul_f32_e32 v32, v38, v66
	v_mul_f32_e32 v32, 0xbfb8aa3b, v32
	v_exp_f32_e32 v32, v32
	s_nop 0
	v_add_f32_e32 v32, 1.0, v32
	v_min_f32_e32 v33, 0x7f7fffff, v32
	v_rcp_f32_e32 v34, v33
	s_nop 0
	v_fma_f32 v35, -v33, v34, 1.0
	v_fmac_f32_e32 v34, v35, v34
	v_mov_b32_e32 v155, v34
	v_mul_f32_e32 v32, v39, v67
	v_mul_f32_e32 v32, 0xbfb8aa3b, v32
	v_exp_f32_e32 v32, v32
	s_nop 0
	v_add_f32_e32 v32, 1.0, v32
	v_min_f32_e32 v33, 0x7f7fffff, v32
	v_rcp_f32_e32 v34, v33
	s_nop 0
	v_fma_f32 v35, -v33, v34, 1.0
	v_fmac_f32_e32 v34, v35, v34
	v_mov_b32_e32 v138, v34
	v_mul_f32_e32 v32, v40, v48
	v_mul_f32_e32 v32, 0xbfb8aa3b, v32
	v_exp_f32_e32 v32, v32
	s_nop 0
	v_add_f32_e32 v32, 1.0, v32
	v_min_f32_e32 v33, 0x7f7fffff, v32
	v_rcp_f32_e32 v34, v33
	s_nop 0
	v_fma_f32 v35, -v33, v34, 1.0
	v_fmac_f32_e32 v34, v35, v34
	v_mov_b32_e32 v139, v34
	v_mul_f32_e32 v32, v41, v49
	v_mul_f32_e32 v32, 0xbfb8aa3b, v32
	v_exp_f32_e32 v32, v32
	s_nop 0
	v_add_f32_e32 v32, 1.0, v32
	v_min_f32_e32 v33, 0x7f7fffff, v32
	v_rcp_f32_e32 v34, v33
	s_nop 0
	v_fma_f32 v35, -v33, v34, 1.0
	v_fmac_f32_e32 v34, v35, v34
	v_mov_b32_e32 v143, v34
	v_mul_f32_e32 v32, v42, v50
	v_mul_f32_e32 v32, 0xbfb8aa3b, v32
	v_exp_f32_e32 v32, v32
	s_nop 0
	v_add_f32_e32 v32, 1.0, v32
	v_min_f32_e32 v33, 0x7f7fffff, v32
	v_rcp_f32_e32 v34, v33
	s_nop 0
	v_fma_f32 v35, -v33, v34, 1.0
	v_fmac_f32_e32 v34, v35, v34
	v_mov_b32_e32 v149, v34
	v_mul_f32_e32 v32, v43, v51
	v_mul_f32_e32 v32, 0xbfb8aa3b, v32
	v_exp_f32_e32 v32, v32
	s_nop 0
	v_add_f32_e32 v32, 1.0, v32
	v_min_f32_e32 v33, 0x7f7fffff, v32
	v_rcp_f32_e32 v34, v33
	s_nop 0
	v_fma_f32 v35, -v33, v34, 1.0
	v_fmac_f32_e32 v34, v35, v34
	v_mov_b32_e32 v140, v34
	v_mul_f32_e32 v32, v44, v52
	v_mul_f32_e32 v32, 0xbfb8aa3b, v32
	v_exp_f32_e32 v32, v32
	s_nop 0
	v_add_f32_e32 v32, 1.0, v32
	v_min_f32_e32 v33, 0x7f7fffff, v32
	v_rcp_f32_e32 v34, v33
	s_nop 0
	v_fma_f32 v35, -v33, v34, 1.0
	v_fmac_f32_e32 v34, v35, v34
	v_mov_b32_e32 v144, v34
	v_mul_f32_e32 v32, v45, v53
	v_mul_f32_e32 v32, 0xbfb8aa3b, v32
	v_exp_f32_e32 v32, v32
	s_nop 0
	v_add_f32_e32 v32, 1.0, v32
	v_min_f32_e32 v33, 0x7f7fffff, v32
	v_rcp_f32_e32 v34, v33
	s_nop 0
	v_fma_f32 v35, -v33, v34, 1.0
	v_fmac_f32_e32 v34, v35, v34
	v_mov_b32_e32 v151, v34
	v_mul_f32_e32 v32, v46, v54
	v_mul_f32_e32 v32, 0xbfb8aa3b, v32
	v_exp_f32_e32 v32, v32
	s_nop 0
	v_add_f32_e32 v32, 1.0, v32
	v_min_f32_e32 v33, 0x7f7fffff, v32
	v_rcp_f32_e32 v34, v33
	s_nop 0
	v_fma_f32 v35, -v33, v34, 1.0
	v_fmac_f32_e32 v34, v35, v34
	v_mov_b32_e32 v154, v34
	v_mul_f32_e32 v32, v47, v55
	v_mul_f32_e32 v32, 0xbfb8aa3b, v32
	v_exp_f32_e32 v32, v32
	s_nop 0
	v_add_f32_e32 v32, 1.0, v32
	v_min_f32_e32 v33, 0x7f7fffff, v32
	v_rcp_f32_e32 v34, v33
	s_nop 0
	v_fma_f32 v35, -v33, v34, 1.0
	v_fmac_f32_e32 v34, v35, v34
	v_mov_b32_e32 v145, v34
	ds_read_b128 v[32:35], v158 offset:55424
	s_waitcnt lgkmcnt(0)
; #define ZERO_ACC(a) ZERO_ACCM(a, 2)
; #define EPI_BEGIN(accv) EPI_BEGINM(accv, 2)
; DI float sigmoidf_(float v) { return 1.f / (1.f + __expf(-v)); }
; DI void phase_ple(const Params& p, int L, char* smem) {
;     ...
;     f32x16 gt[2][2]; ZERO_ACC(gt)
;     gemm_core<true>(p.xb, D, p.wt_pg, D, D, m0, n0, gt, smem);
;     EPI_BEGIN(gt) gt[mt][nt][i] = sigmoidf_(v * rstd_s[rl]); EPI_END
	v_mul_f32_e32 v16, v16, v32
	v_mul_f32_e32 v16, 0xbfb8aa3b, v16
	v_exp_f32_e32 v16, v16
	v_mul_f32_e32 v0, v0, v32
	v_mul_f32_e32 v0, 0xbfb8aa3b, v0
	v_exp_f32_e32 v0, v0
	v_add_f32_e32 v16, 1.0, v16
	v_min_f32_e32 v36, 0x7f7fffff, v16
	v_rcp_f32_e32 v37, v36
	v_add_f32_e32 v0, 1.0, v0
	v_fma_f32 v38, -v36, v37, 1.0
	v_fmac_f32_e32 v37, v38, v37
	v_mov_b32_e32 v141, v37
	v_mul_f32_e32 v16, v17, v33
	v_mul_f32_e32 v16, 0xbfb8aa3b, v16
	v_exp_f32_e32 v16, v16
	s_nop 0
	v_add_f32_e32 v16, 1.0, v16
	v_min_f32_e32 v17, 0x7f7fffff, v16
	v_rcp_f32_e32 v36, v17
	s_nop 0
	v_fma_f32 v37, -v17, v36, 1.0
	v_fmac_f32_e32 v36, v37, v36
	v_mov_b32_e32 v137, v36
	v_mul_f32_e32 v16, v18, v34
	v_mul_f32_e32 v16, 0xbfb8aa3b, v16
	v_exp_f32_e32 v16, v16
	s_nop 0
	v_add_f32_e32 v16, 1.0, v16
	v_min_f32_e32 v17, 0x7f7fffff, v16
	v_rcp_f32_e32 v18, v17
	s_nop 0
	v_fma_f32 v36, -v17, v18, 1.0
	v_fmac_f32_e32 v18, v36, v18
	v_mov_b32_e32 v136, v18
	v_mul_f32_e32 v16, v19, v35
	v_mul_f32_e32 v16, 0xbfb8aa3b, v16
	v_exp_f32_e32 v16, v16
	s_nop 0
	v_add_f32_e32 v16, 1.0, v16
	v_min_f32_e32 v17, 0x7f7fffff, v16
	v_rcp_f32_e32 v18, v17
	s_nop 0
	v_fma_f32 v19, -v17, v18, 1.0
	v_fmac_f32_e32 v18, v19, v18
	v_mov_b32_e32 v126, v18
	ds_read_b128 v[16:19], v158 offset:55456
	s_waitcnt lgkmcnt(0)
	v_mul_f32_e32 v20, v20, v16
	v_mul_f32_e32 v20, 0xbfb8aa3b, v20
	v_exp_f32_e32 v20, v20
	s_nop 0
	v_add_f32_e32 v20, 1.0, v20
	v_min_f32_e32 v36, 0x7f7fffff, v20
	v_rcp_f32_e32 v37, v36
	s_nop 0
	v_fma_f32 v38, -v36, v37, 1.0
	v_fmac_f32_e32 v37, v38, v37
	v_mov_b32_e32 v159, v37
	v_mul_f32_e32 v20, v21, v17
	v_mul_f32_e32 v20, 0xbfb8aa3b, v20
	v_exp_f32_e32 v20, v20
	s_nop 0
	v_add_f32_e32 v20, 1.0, v20
	v_min_f32_e32 v21, 0x7f7fffff, v20
	v_rcp_f32_e32 v36, v21
	s_nop 0
	v_fma_f32 v37, -v21, v36, 1.0
	v_fmac_f32_e32 v36, v37, v36
	v_mov_b32_e32 v160, v36
	v_mul_f32_e32 v20, v22, v18
	v_mul_f32_e32 v20, 0xbfb8aa3b, v20
	v_exp_f32_e32 v20, v20
	s_nop 0
	v_add_f32_e32 v20, 1.0, v20
	v_min_f32_e32 v21, 0x7f7fffff, v20
	v_rcp_f32_e32 v22, v21
	s_nop 0
	v_fma_f32 v36, -v21, v22, 1.0
	v_fmac_f32_e32 v22, v36, v22
	v_mov_b32_e32 v162, v22
	v_mul_f32_e32 v20, v23, v19
	v_mul_f32_e32 v20, 0xbfb8aa3b, v20
	v_exp_f32_e32 v20, v20
	s_nop 0
	v_add_f32_e32 v20, 1.0, v20
	v_min_f32_e32 v21, 0x7f7fffff, v20
	v_rcp_f32_e32 v22, v21
	s_nop 0
	v_fma_f32 v23, -v21, v22, 1.0
	v_fmac_f32_e32 v22, v23, v22
	v_mov_b32_e32 v164, v22
	ds_read_b128 v[20:23], v158 offset:55488
	s_waitcnt lgkmcnt(0)
	v_mul_f32_e32 v24, v24, v20
	v_mul_f32_e32 v24, 0xbfb8aa3b, v24
	v_exp_f32_e32 v24, v24
	s_nop 0
	v_add_f32_e32 v24, 1.0, v24
	v_min_f32_e32 v36, 0x7f7fffff, v24
	v_rcp_f32_e32 v37, v36
	s_nop 0
	v_fma_f32 v38, -v36, v37, 1.0
	v_fmac_f32_e32 v37, v38, v37
	v_mov_b32_e32 v166, v37
	v_mul_f32_e32 v24, v25, v21
	v_mul_f32_e32 v24, 0xbfb8aa3b, v24
	v_exp_f32_e32 v24, v24
	s_nop 0
	v_add_f32_e32 v24, 1.0, v24
	v_min_f32_e32 v25, 0x7f7fffff, v24
	v_rcp_f32_e32 v36, v25
	s_nop 0
	v_fma_f32 v37, -v25, v36, 1.0
	v_fmac_f32_e32 v36, v37, v36
	v_mov_b32_e32 v167, v36
	v_mul_f32_e32 v24, v26, v22
	v_mul_f32_e32 v24, 0xbfb8aa3b, v24
	v_exp_f32_e32 v24, v24
	s_nop 0
	v_add_f32_e32 v24, 1.0, v24
	v_min_f32_e32 v25, 0x7f7fffff, v24
	v_rcp_f32_e32 v26, v25
	s_nop 0
	v_fma_f32 v36, -v25, v26, 1.0
	v_fmac_f32_e32 v26, v36, v26
	v_mov_b32_e32 v168, v26
	v_mul_f32_e32 v24, v27, v23
	v_mul_f32_e32 v24, 0xbfb8aa3b, v24
	v_exp_f32_e32 v24, v24
	s_nop 0
	v_add_f32_e32 v24, 1.0, v24
	v_min_f32_e32 v25, 0x7f7fffff, v24
	v_rcp_f32_e32 v26, v25
	s_nop 0
	v_fma_f32 v27, -v25, v26, 1.0
	v_fmac_f32_e32 v26, v27, v26
	v_mov_b32_e32 v169, v26
	ds_read_b128 v[24:27], v158 offset:55520
	s_waitcnt lgkmcnt(0)
	v_mul_f32_e32 v28, v28, v24
	v_mul_f32_e32 v28, 0xbfb8aa3b, v28
	v_exp_f32_e32 v28, v28
	s_nop 0
	v_add_f32_e32 v28, 1.0, v28
	v_min_f32_e32 v36, 0x7f7fffff, v28
	v_rcp_f32_e32 v37, v36
	s_nop 0
	v_fma_f32 v38, -v36, v37, 1.0
	v_fmac_f32_e32 v37, v38, v37
	v_mov_b32_e32 v174, v37
	v_mul_f32_e32 v28, v29, v25
	v_mul_f32_e32 v28, 0xbfb8aa3b, v28
	v_exp_f32_e32 v28, v28
	s_nop 0
	v_add_f32_e32 v28, 1.0, v28
	v_min_f32_e32 v29, 0x7f7fffff, v28
	v_rcp_f32_e32 v36, v29
	s_nop 0
	v_fma_f32 v37, -v29, v36, 1.0
	v_fmac_f32_e32 v36, v37, v36
	v_mov_b32_e32 v175, v36
	v_mul_f32_e32 v28, v30, v26
	v_mul_f32_e32 v28, 0xbfb8aa3b, v28
	v_exp_f32_e32 v28, v28
	s_nop 0
	v_add_f32_e32 v28, 1.0, v28
	v_min_f32_e32 v29, 0x7f7fffff, v28
	v_rcp_f32_e32 v30, v29
	s_nop 0
	v_fma_f32 v36, -v29, v30, 1.0
	v_fmac_f32_e32 v30, v36, v30
	v_mov_b32_e32 v176, v30
	v_mul_f32_e32 v28, v31, v27
	v_mul_f32_e32 v28, 0xbfb8aa3b, v28
	v_exp_f32_e32 v28, v28
	s_nop 0
	v_add_f32_e32 v28, 1.0, v28
	v_min_f32_e32 v29, 0x7f7fffff, v28
	v_rcp_f32_e32 v30, v29
	s_nop 0
	v_fma_f32 v31, -v29, v30, 1.0
	v_fmac_f32_e32 v30, v31, v30
	v_mov_b32_e32 v177, v30
	v_min_f32_e32 v28, 0x7f7fffff, v0
	v_rcp_f32_e32 v29, v28
	s_nop 0
	v_fma_f32 v30, -v28, v29, 1.0
	v_fmac_f32_e32 v29, v30, v29
	v_mov_b32_e32 v178, v29
	v_mul_f32_e32 v0, v1, v33
	v_mul_f32_e32 v0, 0xbfb8aa3b, v0
	v_exp_f32_e32 v0, v0
	v_mov_b32_e32 v32, v224
	v_add_f32_e32 v0, 1.0, v0
	v_min_f32_e32 v1, 0x7f7fffff, v0
	v_rcp_f32_e32 v28, v1
	v_ashrrev_i32_e32 v33, 3, v32
	v_lshrrev_b32_e32 v37, 1, v32
	v_and_b32_e32 v36, 0x5f, v32
	v_fma_f32 v29, -v1, v28, 1.0
	v_fmac_f32_e32 v28, v29, v28
	v_mov_b32_e32 v179, v28
	v_mul_f32_e32 v0, v2, v34
	v_mul_f32_e32 v0, 0xbfb8aa3b, v0
	v_exp_f32_e32 v0, v0
	s_nop 0
	v_add_f32_e32 v0, 1.0, v0
	v_min_f32_e32 v1, 0x7f7fffff, v0
	v_rcp_f32_e32 v2, v1
	s_nop 0
	v_fma_f32 v28, -v1, v2, 1.0
	v_fmac_f32_e32 v2, v28, v2
	v_mov_b32_e32 v180, v2
	v_mul_f32_e32 v0, v3, v35
	v_mul_f32_e32 v0, 0xbfb8aa3b, v0
; DI float sigmoidf_(float v) { return 1.f / (1.f + __expf(-v)); }
; #define ZERO_ACC(a) ZERO_ACCM(a, 2)
; #define EPI_BEGIN(accv) EPI_BEGINM(accv, 2)
; template <bool NORM, bool DEEP, int MTW, int KSEG, class HOOK>
; DI void gemm_core_h(const bfu* __restrict__ A, int lda, const bfu* __restrict__ Bt, int ldb, int K, int m0, int n0,
;                     f32x16 (&acc)[MTW][2], char* smem, HOOK hook) {
;     ...
;   u32x4 ra0[NA], rb0[4], ra1[NA], rb1[4];
;   float ssq[NA];
; #pragma unroll
;   for (int j = 0; j < NA; ++j) ssq[j] = 0.f;
;   const int nk = K >> 6;
; #pragma unroll
;   for (int j = 0; j < NA; ++j) ra0[j] = *(const u32x4*)AP_(j, 0);
; #pragma unroll
;   for (int j = 0; j < 4; ++j) rb0[j] = *(const u32x4*)BP_(j, 0);
;   if (DEEP) {
; #pragma unroll
;     for (int j = 0; j < NA; ++j) ra1[j] = *(const u32x4*)AP_(j, 64);
; #pragma unroll
;     for (int j = 0; j < 4; ++j) rb1[j] = *(const u32x4*)BP_(j, 64);
;   }
; DI void phase_ple(const Params& p, int L, char* smem) {
;     ...
;     EPI_BEGIN(gt) gt[mt][nt][i] = sigmoidf_(v * rstd_s[rl]); EPI_END
;     f32x16 acc[2][2]; ZERO_ACC(acc)
;     gemm_core<false, false>(p.pb, 256, p.wt_pp, 256, 256, m0, n0, acc, smem);
	v_exp_f32_e32 v0, v0
	v_and_b32_e32 v35, 31, v32
	v_and_or_b32 v35, v37, s7, v35
	v_add_f32_e32 v0, 1.0, v0
	v_min_f32_e32 v1, 0x7f7fffff, v0
	v_rcp_f32_e32 v2, v1
	s_nop 0
	v_fma_f32 v3, -v1, v2, 1.0
	v_fmac_f32_e32 v2, v3, v2
	v_mov_b32_e32 v146, v2
	v_mul_f32_e32 v0, v4, v16
	v_mul_f32_e32 v0, 0xbfb8aa3b, v0
	v_exp_f32_e32 v0, v0
	v_mov_b32_e32 v29, v189
	v_add_f32_e32 v0, 1.0, v0
	v_min_f32_e32 v1, 0x7f7fffff, v0
	v_rcp_f32_e32 v2, v1
	s_nop 0
	v_fma_f32 v3, -v1, v2, 1.0
	v_fmac_f32_e32 v2, v3, v2
	v_mov_b32_e32 v147, v2
	v_mul_f32_e32 v0, v5, v17
	v_mul_f32_e32 v0, 0xbfb8aa3b, v0
	v_exp_f32_e32 v0, v0
	v_add_u32_e32 v16, s10, v33
	v_add_f32_e32 v0, 1.0, v0
	v_min_f32_e32 v1, 0x7f7fffff, v0
	v_rcp_f32_e32 v2, v1
	s_nop 0
	v_fma_f32 v3, -v1, v2, 1.0
	v_fmac_f32_e32 v2, v3, v2
	v_mov_b32_e32 v150, v2
	v_mul_f32_e32 v0, v6, v18
	v_mul_f32_e32 v0, 0xbfb8aa3b, v0
	v_exp_f32_e32 v0, v0
	s_nop 0
	v_add_f32_e32 v0, 1.0, v0
	v_min_f32_e32 v1, 0x7f7fffff, v0
	v_rcp_f32_e32 v2, v1
	s_nop 0
	v_fma_f32 v3, -v1, v2, 1.0
	v_fmac_f32_e32 v2, v3, v2
	v_mov_b32_e32 v152, v2
	v_mul_f32_e32 v0, v7, v19
	v_mul_f32_e32 v0, 0xbfb8aa3b, v0
	v_exp_f32_e32 v0, v0
	s_nop 0
	v_add_f32_e32 v0, 1.0, v0
	v_min_f32_e32 v1, 0x7f7fffff, v0
	v_rcp_f32_e32 v2, v1
	s_nop 0
	v_fma_f32 v3, -v1, v2, 1.0
	v_fmac_f32_e32 v2, v3, v2
	v_mov_b32_e32 v127, v2
	v_mul_f32_e32 v0, v8, v20
	v_mul_f32_e32 v0, 0xbfb8aa3b, v0
	v_exp_f32_e32 v0, v0
	s_nop 0
	v_add_f32_e32 v0, 1.0, v0
	v_min_f32_e32 v1, 0x7f7fffff, v0
	v_rcp_f32_e32 v2, v1
	s_nop 0
	v_fma_f32 v3, -v1, v2, 1.0
	v_fmac_f32_e32 v2, v3, v2
	v_mov_b32_e32 v129, v2
	v_mul_f32_e32 v0, v9, v21
	v_mul_f32_e32 v0, 0xbfb8aa3b, v0
	v_exp_f32_e32 v0, v0
	v_mov_b32_e32 v9, v189
	v_mov_b32_e32 v21, v189
	v_add_f32_e32 v0, 1.0, v0
	v_min_f32_e32 v1, 0x7f7fffff, v0
	v_rcp_f32_e32 v2, v1
	s_nop 0
	v_fma_f32 v3, -v1, v2, 1.0
	v_fmac_f32_e32 v2, v3, v2
	v_mov_b32_e32 v130, v2
	v_mul_f32_e32 v0, v10, v22
	v_mul_f32_e32 v0, 0xbfb8aa3b, v0
	v_exp_f32_e32 v0, v0
	s_nop 0
	v_add_f32_e32 v0, 1.0, v0
	v_min_f32_e32 v1, 0x7f7fffff, v0
	v_rcp_f32_e32 v2, v1
	s_nop 0
	v_fma_f32 v3, -v1, v2, 1.0
	v_fmac_f32_e32 v2, v3, v2
	v_mov_b32_e32 v131, v2
	v_mul_f32_e32 v0, v11, v23
	v_mul_f32_e32 v0, 0xbfb8aa3b, v0
	v_exp_f32_e32 v0, v0
	s_nop 0
	v_add_f32_e32 v0, 1.0, v0
	v_min_f32_e32 v1, 0x7f7fffff, v0
	v_rcp_f32_e32 v2, v1
	s_nop 0
	v_fma_f32 v3, -v1, v2, 1.0
	v_fmac_f32_e32 v2, v3, v2
	v_mov_b32_e32 v120, v2
	v_mul_f32_e32 v0, v12, v24
	v_mul_f32_e32 v0, 0xbfb8aa3b, v0
	v_exp_f32_e32 v0, v0
	s_nop 0
	v_add_f32_e32 v0, 1.0, v0
	v_min_f32_e32 v1, 0x7f7fffff, v0
	v_rcp_f32_e32 v2, v1
	s_nop 0
	v_fma_f32 v3, -v1, v2, 1.0
	v_fmac_f32_e32 v2, v3, v2
	v_mov_b32_e32 v121, v2
	v_mul_f32_e32 v0, v13, v25
	v_mul_f32_e32 v0, 0xbfb8aa3b, v0
	v_exp_f32_e32 v0, v0
	v_mov_b32_e32 v13, v189
	v_mov_b32_e32 v25, v189
	v_add_f32_e32 v0, 1.0, v0
	v_min_f32_e32 v1, 0x7f7fffff, v0
	v_rcp_f32_e32 v2, v1
	s_nop 0
	v_fma_f32 v3, -v1, v2, 1.0
	v_fmac_f32_e32 v2, v3, v2
	v_mov_b32_e32 v122, v2
	v_mul_f32_e32 v0, v14, v26
	v_mul_f32_e32 v0, 0xbfb8aa3b, v0
	v_exp_f32_e32 v0, v0
	s_nop 0
	v_add_f32_e32 v0, 1.0, v0
	v_min_f32_e32 v1, 0x7f7fffff, v0
	v_rcp_f32_e32 v2, v1
	s_nop 0
	v_fma_f32 v3, -v1, v2, 1.0
	v_fmac_f32_e32 v2, v3, v2
	v_mov_b32_e32 v124, v2
	v_mul_f32_e32 v0, v15, v27
	v_mul_f32_e32 v0, 0xbfb8aa3b, v0
	v_exp_f32_e32 v0, v0
	s_nop 0
	v_add_f32_e32 v0, 1.0, v0
	v_min_f32_e32 v1, 0x7f7fffff, v0
	v_rcp_f32_e32 v2, v1
	s_nop 0
	v_fma_f32 v3, -v1, v2, 1.0
	v_fmac_f32_e32 v2, v3, v2
	v_mov_b32_e32 v116, v2
	v_lshlrev_b32_e32 v1, 3, v32
	v_add_u32_e32 v0, s9, v33
	v_and_b32_e32 v34, 56, v1
	v_lshl_or_b32 v188, v0, 8, v34
	v_lshl_add_u64 v[102:103], v[188:189], 1, s[42:43]
	v_add_u32_e32 v4, 0x2000, v188
	v_mov_b32_e32 v5, v189
	global_load_dwordx4 v[0:3], v[102:103], off
	v_lshl_add_u64 v[4:5], v[4:5], 1, s[42:43]
	v_add_u32_e32 v8, 0x4000, v188
	global_load_dwordx4 v[4:7], v[4:5], off
	v_lshl_add_u64 v[8:9], v[8:9], 1, s[42:43]
	v_add_u32_e32 v12, 0x6000, v188
	global_load_dwordx4 v[8:11], v[8:9], off
	v_lshl_add_u64 v[12:13], v[12:13], 1, s[42:43]
	v_lshl_or_b32 v104, v16, 8, v34
	global_load_dwordx4 v[12:15], v[12:13], off
	v_lshl_add_u64 v[106:107], v[104:105], 1, s[30:31]
	v_add_u32_e32 v20, 0x2000, v104
	global_load_dwordx4 v[16:19], v[106:107], off
	v_lshl_add_u64 v[20:21], v[20:21], 1, s[30:31]
	v_add_u32_e32 v24, 0x4000, v104
	global_load_dwordx4 v[20:23], v[20:21], off
	v_lshl_add_u64 v[24:25], v[24:25], 1, s[30:31]
	v_add_u32_e32 v28, 0x6000, v104
	global_load_dwordx4 v[24:27], v[24:25], off
	v_lshl_add_u64 v[28:29], v[28:29], 1, s[30:31]
	global_load_dwordx4 v[28:31], v[28:29], off
	v_and_b32_e32 v32, 16, v37
	v_mad_u32_u24 v105, v36, s6, v32
	v_mad_u64_u32 v[100:101], s[2:3], v35, s6, v[32:33]
	v_mul_lo_u32 v32, v33, s6
	v_lshl_add_u32 v101, v34, 1, v32
	s_waitcnt lgkmcnt(0)
	s_barrier
	s_waitcnt vmcnt(7)
	ds_write_b128 v101, v[0:3]
	s_waitcnt vmcnt(6)
	ds_write_b128 v101, v[4:7] offset:4608
	s_waitcnt vmcnt(5)
	ds_write_b128 v101, v[8:11] offset:9216
	s_waitcnt vmcnt(4)
	ds_write_b128 v101, v[12:15] offset:13824
	s_waitcnt vmcnt(3)
	ds_write_b128 v101, v[16:19] offset:18432
	s_waitcnt vmcnt(2)
	ds_write_b128 v101, v[20:23] offset:23040
	s_waitcnt vmcnt(1)
	ds_write_b128 v101, v[24:27] offset:27648
	s_waitcnt vmcnt(0)
	ds_write_b128 v101, v[28:31] offset:32256
	v_add_u32_e32 v0, 0x2040, v188
	v_mov_b32_e32 v1, v189
	s_waitcnt lgkmcnt(0)
	s_barrier
	v_lshl_add_u64 v[0:1], v[0:1], 1, s[42:43]
	global_load_dwordx4 v[64:67], v[102:103], off offset:128
	global_load_dwordx4 v[68:71], v[0:1], off
	v_add_u32_e32 v0, 0x4040, v188
	v_mov_b32_e32 v1, v189
	v_lshl_add_u64 v[0:1], v[0:1], 1, s[42:43]
	global_load_dwordx4 v[72:75], v[0:1], off
	v_add_u32_e32 v0, 0x6040, v188
	v_mov_b32_e32 v1, v189
	v_lshl_add_u64 v[0:1], v[0:1], 1, s[42:43]
	global_load_dwordx4 v[76:79], v[0:1], off
	global_load_dwordx4 v[80:83], v[106:107], off offset:128
	v_add_u32_e32 v0, 0x2040, v104
	v_mov_b32_e32 v1, v189
	v_lshl_add_u64 v[0:1], v[0:1], 1, s[30:31]
	global_load_dwordx4 v[84:87], v[0:1], off
	v_add_u32_e32 v0, 0x4040, v104
	v_mov_b32_e32 v1, v189
	v_lshl_add_u64 v[0:1], v[0:1], 1, s[30:31]
	global_load_dwordx4 v[88:91], v[0:1], off
	v_add_u32_e32 v0, 0x6040, v104
	v_mov_b32_e32 v1, v189
	v_lshl_add_u64 v[0:1], v[0:1], 1, s[30:31]
	global_load_dwordx4 v[92:95], v[0:1], off
	ds_read_b128 v[0:3], v105 offset:23040
	ds_read_b128 v[4:7], v105 offset:18432
	ds_read_b128 v[96:99], v105 offset:18464
	ds_read_b128 v[8:11], v100
	ds_read_b128 v[182:185], v100 offset:32
	s_waitcnt lgkmcnt(1)
	v_mfma_f32_32x32x16_bf16 v[48:63], v[8:11], v[4:7], 0
	ds_read_b128 v[190:193], v105 offset:23072
	v_readlane_b32 s2, v254, 38
	v_readlane_b32 s3, v254, 39
	v_mfma_f32_32x32x16_bf16 v[32:47], v[8:11], v[0:3], 0
	ds_read_b128 v[8:11], v100 offset:4608
	s_waitcnt lgkmcnt(2)
	v_mfma_f32_32x32x16_bf16 v[48:63], v[182:185], v[96:99], v[48:63]
	s_waitcnt lgkmcnt(1)
	v_mfma_f32_32x32x16_bf16 v[32:47], v[182:185], v[190:193], v[32:47]
	ds_read_b128 v[182:185], v100 offset:4640
	s_waitcnt lgkmcnt(1)
	v_mfma_f32_32x32x16_bf16 v[16:31], v[8:11], v[4:7], 0
	v_mfma_f32_32x32x16_bf16 v[0:15], v[8:11], v[0:3], 0
	s_waitcnt lgkmcnt(0)
	v_mfma_f32_32x32x16_bf16 v[16:31], v[182:185], v[96:99], v[16:31]
	v_mfma_f32_32x32x16_bf16 v[0:15], v[182:185], v[190:193], v[0:15]
	ds_read_b128 v[96:99], v105 offset:18496
	ds_read_b128 v[182:185], v105 offset:23104
	ds_read_b128 v[190:193], v100 offset:64
	s_waitcnt lgkmcnt(0)
	v_mfma_f32_32x32x16_bf16 v[48:63], v[190:193], v[96:99], v[48:63]
	v_mfma_f32_32x32x16_bf16 v[32:47], v[190:193], v[182:185], v[32:47]
	ds_read_b128 v[190:193], v100 offset:4672
	s_waitcnt lgkmcnt(0)
	v_mfma_f32_32x32x16_bf16 v[16:31], v[190:193], v[96:99], v[16:31]
	v_mfma_f32_32x32x16_bf16 v[0:15], v[190:193], v[182:185], v[0:15]
	ds_read_b128 v[96:99], v105 offset:18528
	ds_read_b128 v[182:185], v105 offset:23136
	ds_read_b128 v[190:193], v100 offset:96
	s_waitcnt lgkmcnt(0)
	v_mfma_f32_32x32x16_bf16 v[48:63], v[190:193], v[96:99], v[48:63]
	v_mfma_f32_32x32x16_bf16 v[32:47], v[190:193], v[182:185], v[32:47]
	ds_read_b128 v[190:193], v100 offset:4704
	s_waitcnt lgkmcnt(0)
	s_barrier
	s_waitcnt vmcnt(7)
	ds_write_b128 v101, v[64:67]
	s_waitcnt vmcnt(6)
	ds_write_b128 v101, v[68:71] offset:4608
	s_waitcnt vmcnt(5)
	ds_write_b128 v101, v[72:75] offset:9216
	s_waitcnt vmcnt(4)
	ds_write_b128 v101, v[76:79] offset:13824
	s_waitcnt vmcnt(3)
	ds_write_b128 v101, v[80:83] offset:18432
	s_waitcnt vmcnt(2)
	ds_write_b128 v101, v[84:87] offset:23040
	s_waitcnt vmcnt(1)
	ds_write_b128 v101, v[88:91] offset:27648
	s_waitcnt vmcnt(0)
	ds_write_b128 v101, v[92:95] offset:32256
	v_add_u32_e32 v68, 0x2080, v188
	v_mov_b32_e32 v69, v189
	v_add_u32_e32 v72, 0x4080, v188
	v_mov_b32_e32 v73, v189
	v_add_u32_e32 v76, 0x6080, v188
	v_mov_b32_e32 v77, v189
	s_waitcnt lgkmcnt(0)
	s_barrier
	v_lshl_add_u64 v[68:69], v[68:69], 1, s[42:43]
	v_lshl_add_u64 v[72:73], v[72:73], 1, s[42:43]
	v_lshl_add_u64 v[76:77], v[76:77], 1, s[42:43]
	global_load_dwordx4 v[64:67], v[102:103], off offset:256
	v_add_u32_e32 v84, 0x2080, v104
	global_load_dwordx4 v[68:71], v[68:69], off
	v_mov_b32_e32 v85, v189
	global_load_dwordx4 v[72:75], v[72:73], off
	s_nop 0
	global_load_dwordx4 v[76:79], v[76:77], off
	s_nop 0
	global_load_dwordx4 v[80:83], v[106:107], off offset:256
	v_lshl_add_u64 v[84:85], v[84:85], 1, s[30:31]
	v_add_u32_e32 v88, 0x4080, v104
	v_mov_b32_e32 v89, v189
	global_load_dwordx4 v[84:87], v[84:85], off
	v_lshl_add_u64 v[88:89], v[88:89], 1, s[30:31]
	v_add_u32_e32 v92, 0x6080, v104
	v_mov_b32_e32 v93, v189
	global_load_dwordx4 v[88:91], v[88:89], off
	v_lshl_add_u64 v[92:93], v[92:93], 1, s[30:31]
	global_load_dwordx4 v[92:95], v[92:93], off
	s_waitcnt lgkmcnt(8)
	v_mfma_f32_32x32x16_bf16 v[16:31], v[190:193], v[96:99], v[16:31]
	v_mfma_f32_32x32x16_bf16 v[0:15], v[190:193], v[182:185], v[0:15]
	ds_read_b128 v[182:185], v105 offset:23040
	ds_read_b128 v[190:193], v105 offset:18432
	ds_read_b128 v[96:99], v105 offset:18464
	ds_read_b128 v[194:197], v100
	ds_read_b128 v[198:201], v100 offset:32
	s_waitcnt lgkmcnt(1)
	v_mfma_f32_32x32x16_bf16 v[48:63], v[194:197], v[190:193], v[48:63]
	v_mfma_f32_32x32x16_bf16 v[32:47], v[194:197], v[182:185], v[32:47]
	ds_read_b128 v[194:197], v100 offset:4608
	s_waitcnt lgkmcnt(0)
	v_mfma_f32_32x32x16_bf16 v[16:31], v[194:197], v[190:193], v[16:31]
	ds_read_b128 v[190:193], v100 offset:4640
	v_mfma_f32_32x32x16_bf16 v[0:15], v[194:197], v[182:185], v[0:15]
	ds_read_b128 v[182:185], v105 offset:23072
	v_mfma_f32_32x32x16_bf16 v[48:63], v[198:201], v[96:99], v[48:63]
	s_waitcnt lgkmcnt(0)
	v_mfma_f32_32x32x16_bf16 v[32:47], v[198:201], v[182:185], v[32:47]
	v_mfma_f32_32x32x16_bf16 v[16:31], v[190:193], v[96:99], v[16:31]
	v_mfma_f32_32x32x16_bf16 v[0:15], v[190:193], v[182:185], v[0:15]
	ds_read_b128 v[96:99], v105 offset:18496
	ds_read_b128 v[182:185], v105 offset:23104
	ds_read_b128 v[190:193], v100 offset:64
	s_waitcnt lgkmcnt(0)
	v_mfma_f32_32x32x16_bf16 v[48:63], v[190:193], v[96:99], v[48:63]
	v_mfma_f32_32x32x16_bf16 v[32:47], v[190:193], v[182:185], v[32:47]
	ds_read_b128 v[190:193], v100 offset:4672
	s_waitcnt lgkmcnt(0)
	v_mfma_f32_32x32x16_bf16 v[16:31], v[190:193], v[96:99], v[16:31]
	v_mfma_f32_32x32x16_bf16 v[0:15], v[190:193], v[182:185], v[0:15]
	ds_read_b128 v[96:99], v105 offset:18528
	ds_read_b128 v[182:185], v105 offset:23136
	ds_read_b128 v[190:193], v100 offset:96
	s_waitcnt lgkmcnt(0)
	v_mfma_f32_32x32x16_bf16 v[48:63], v[190:193], v[96:99], v[48:63]
	v_mfma_f32_32x32x16_bf16 v[32:47], v[190:193], v[182:185], v[32:47]
	ds_read_b128 v[190:193], v100 offset:4704
	s_waitcnt lgkmcnt(0)
	s_barrier
	s_waitcnt vmcnt(7)
	ds_write_b128 v101, v[64:67]
	s_waitcnt vmcnt(6)
	ds_write_b128 v101, v[68:71] offset:4608
	s_waitcnt vmcnt(5)
	ds_write_b128 v101, v[72:75] offset:9216
	s_waitcnt vmcnt(4)
	ds_write_b128 v101, v[76:79] offset:13824
	s_waitcnt vmcnt(3)
	ds_write_b128 v101, v[80:83] offset:18432
	s_waitcnt vmcnt(2)
	ds_write_b128 v101, v[84:87] offset:23040
	s_waitcnt vmcnt(1)
	ds_write_b128 v101, v[88:91] offset:27648
	s_waitcnt vmcnt(0)
	ds_write_b128 v101, v[92:95] offset:32256
	v_add_u32_e32 v68, 0x20c0, v188
	v_mov_b32_e32 v69, v189
	v_add_u32_e32 v72, 0x40c0, v188
	v_mov_b32_e32 v73, v189
	v_add_u32_e32 v188, 0x60c0, v188
	s_waitcnt lgkmcnt(0)
	s_barrier
	v_lshl_add_u64 v[68:69], v[68:69], 1, s[42:43]
	v_lshl_add_u64 v[72:73], v[72:73], 1, s[42:43]
	v_lshl_add_u64 v[76:77], v[188:189], 1, s[42:43]
	global_load_dwordx4 v[64:67], v[102:103], off offset:384
	v_add_u32_e32 v188, 0x20c0, v104
	global_load_dwordx4 v[68:71], v[68:69], off
	v_lshl_add_u64 v[84:85], v[188:189], 1, s[30:31]
	global_load_dwordx4 v[72:75], v[72:73], off
	s_nop 0
	global_load_dwordx4 v[76:79], v[76:77], off
	s_nop 0
	global_load_dwordx4 v[80:83], v[106:107], off offset:384
	v_add_u32_e32 v188, 0x40c0, v104
	global_load_dwordx4 v[84:87], v[84:85], off
	v_lshl_add_u64 v[88:89], v[188:189], 1, s[30:31]
	v_add_u32_e32 v188, 0x60c0, v104
	global_load_dwordx4 v[88:91], v[88:89], off
	v_lshl_add_u64 v[92:93], v[188:189], 1, s[30:31]
	global_load_dwordx4 v[92:95], v[92:93], off
	s_waitcnt lgkmcnt(8)
	v_mfma_f32_32x32x16_bf16 v[16:31], v[190:193], v[96:99], v[16:31]
	v_mfma_f32_32x32x16_bf16 v[0:15], v[190:193], v[182:185], v[0:15]
	ds_read_b128 v[106:109], v105 offset:23040
	ds_read_b128 v[182:185], v105 offset:18432
	ds_read_b128 v[96:99], v105 offset:18464
	ds_read_b128 v[190:193], v100
	ds_read_b128 v[194:197], v100 offset:32
	s_waitcnt lgkmcnt(1)
	v_mfma_f32_32x32x16_bf16 v[48:63], v[190:193], v[182:185], v[48:63]
	v_mfma_f32_32x32x16_bf16 v[32:47], v[190:193], v[106:109], v[32:47]
	ds_read_b128 v[190:193], v100 offset:4608
	s_waitcnt lgkmcnt(0)
	v_mfma_f32_32x32x16_bf16 v[16:31], v[190:193], v[182:185], v[16:31]
	ds_read_b128 v[182:185], v100 offset:4640
	v_mfma_f32_32x32x16_bf16 v[0:15], v[190:193], v[106:109], v[0:15]
	ds_read_b128 v[106:109], v105 offset:23072
	v_mfma_f32_32x32x16_bf16 v[48:63], v[194:197], v[96:99], v[48:63]
	s_waitcnt lgkmcnt(0)
	v_mfma_f32_32x32x16_bf16 v[32:47], v[194:197], v[106:109], v[32:47]
	v_mfma_f32_32x32x16_bf16 v[16:31], v[182:185], v[96:99], v[16:31]
	v_mfma_f32_32x32x16_bf16 v[0:15], v[182:185], v[106:109], v[0:15]
	ds_read_b128 v[96:99], v105 offset:18496
	ds_read_b128 v[106:109], v105 offset:23104
	ds_read_b128 v[182:185], v100 offset:64
	s_waitcnt lgkmcnt(0)
	v_mfma_f32_32x32x16_bf16 v[48:63], v[182:185], v[96:99], v[48:63]
	v_mfma_f32_32x32x16_bf16 v[32:47], v[182:185], v[106:109], v[32:47]
	ds_read_b128 v[182:185], v100 offset:4672
	s_waitcnt lgkmcnt(0)
	v_mfma_f32_32x32x16_bf16 v[16:31], v[182:185], v[96:99], v[16:31]
	v_mfma_f32_32x32x16_bf16 v[0:15], v[182:185], v[106:109], v[0:15]
	ds_read_b128 v[96:99], v105 offset:18528
	ds_read_b128 v[106:109], v105 offset:23136
	ds_read_b128 v[182:185], v100 offset:96
	s_waitcnt lgkmcnt(0)
	v_mfma_f32_32x32x16_bf16 v[48:63], v[182:185], v[96:99], v[48:63]
	v_mfma_f32_32x32x16_bf16 v[32:47], v[182:185], v[106:109], v[32:47]
	ds_read_b128 v[182:185], v100 offset:4704
	s_waitcnt lgkmcnt(0)
	s_barrier
	s_waitcnt vmcnt(7)
	ds_write_b128 v101, v[64:67]
	s_waitcnt vmcnt(6)
	ds_write_b128 v101, v[68:71] offset:4608
	s_waitcnt vmcnt(5)
	ds_write_b128 v101, v[72:75] offset:9216
	s_waitcnt vmcnt(4)
	ds_write_b128 v101, v[76:79] offset:13824
	s_waitcnt vmcnt(3)
	ds_write_b128 v101, v[80:83] offset:18432
	s_waitcnt vmcnt(2)
	ds_write_b128 v101, v[84:87] offset:23040
	s_waitcnt vmcnt(1)
	ds_write_b128 v101, v[88:91] offset:27648
	s_waitcnt vmcnt(0)
	ds_write_b128 v101, v[92:95] offset:32256
	s_waitcnt lgkmcnt(0)
	s_barrier
	ds_read_b128 v[64:67], v105 offset:23040
	ds_read_b128 v[68:71], v105 offset:18432
	ds_read_b128 v[72:75], v105 offset:18464
	ds_read_b128 v[76:79], v100
	ds_read_b128 v[80:83], v100 offset:32
	s_waitcnt lgkmcnt(1)
	v_mfma_f32_32x32x16_bf16 v[48:63], v[76:79], v[68:71], v[48:63]
	v_mfma_f32_32x32x16_bf16 v[32:47], v[76:79], v[64:67], v[32:47]
	ds_read_b128 v[76:79], v100 offset:4608
	v_mfma_f32_32x32x16_bf16 v[16:31], v[182:185], v[96:99], v[16:31]
	v_mfma_f32_32x32x16_bf16 v[0:15], v[182:185], v[106:109], v[0:15]
	s_waitcnt lgkmcnt(0)
	v_mfma_f32_32x32x16_bf16 v[16:31], v[76:79], v[68:71], v[16:31]
	ds_read_b128 v[68:71], v100 offset:4640
	v_mfma_f32_32x32x16_bf16 v[0:15], v[76:79], v[64:67], v[0:15]
	ds_read_b128 v[64:67], v105 offset:23072
	v_mfma_f32_32x32x16_bf16 v[48:63], v[80:83], v[72:75], v[48:63]
	s_waitcnt lgkmcnt(0)
	v_mfma_f32_32x32x16_bf16 v[32:47], v[80:83], v[64:67], v[32:47]
	v_mfma_f32_32x32x16_bf16 v[16:31], v[68:71], v[72:75], v[16:31]
	v_mfma_f32_32x32x16_bf16 v[0:15], v[68:71], v[64:67], v[0:15]
	ds_read_b128 v[64:67], v105 offset:18496
	ds_read_b128 v[68:71], v105 offset:23104
	ds_read_b128 v[72:75], v100 offset:64
	s_waitcnt lgkmcnt(0)
	v_mfma_f32_32x32x16_bf16 v[48:63], v[72:75], v[64:67], v[48:63]
	v_mfma_f32_32x32x16_bf16 v[32:47], v[72:75], v[68:71], v[32:47]
	ds_read_b128 v[72:75], v100 offset:4672
	s_waitcnt lgkmcnt(0)
	v_mfma_f32_32x32x16_bf16 v[16:31], v[72:75], v[64:67], v[16:31]
	v_mfma_f32_32x32x16_bf16 v[0:15], v[72:75], v[68:71], v[0:15]
	ds_read_b128 v[64:67], v105 offset:18528
	ds_read_b128 v[68:71], v105 offset:23136
	ds_read_b128 v[72:75], v100 offset:96
	s_waitcnt lgkmcnt(0)
	v_mfma_f32_32x32x16_bf16 v[48:63], v[72:75], v[64:67], v[48:63]
	v_mfma_f32_32x32x16_bf16 v[32:47], v[72:75], v[68:71], v[32:47]
	ds_read_b128 v[72:75], v100 offset:4704
	s_waitcnt lgkmcnt(0)
	s_barrier
; #define EPI_BEGIN(accv) EPI_BEGINM(accv, 2)
; DI void phase_ple(const Params& p, int L, char* smem) {
;     ...
;     EPI_BEGIN(acc)
;       float* xp = p.out + (size_t)row * 1024 + col;
;       float nv = *xp + gt[mt][nt][i] * v; *xp = nv; p.xb2[(size_t)row * 1024 + col] = f2bf(nv);
;     EPI_END
	v_mfma_f32_32x32x16_bf16 v[16:31], v[72:75], v[64:67], v[16:31]
	v_mfma_f32_32x32x16_bf16 v[0:15], v[72:75], v[68:71], v[0:15]
	v_add_u32_e32 v186, s9, v156
	v_or_b32_e32 v187, s10, v157
	v_lshlrev_b32_e32 v186, 12, v186
	v_lshl_add_u32 v186, v187, 2, v186
	v_lshrrev_b32_e32 v187, 1, v186
	global_load_dword v76, v186, s[64:65]
	global_load_dword v77, v186, s[64:65] offset:128
	v_add_u32_e32 v220, 0x1000, v186
	global_load_dword v78, v220, s[64:65]
	global_load_dword v79, v220, s[64:65] offset:128
	v_add_u32_e32 v220, 0x2000, v186
	global_load_dword v80, v220, s[64:65]
	global_load_dword v81, v220, s[64:65] offset:128
	v_add_u32_e32 v220, 0x3000, v186
	global_load_dword v82, v220, s[64:65]
	global_load_dword v83, v220, s[64:65] offset:128
	v_add_u32_e32 v220, 0x8000, v186
	global_load_dword v84, v220, s[64:65]
	global_load_dword v85, v220, s[64:65] offset:128
	v_add_u32_e32 v220, 0x9000, v186
	global_load_dword v86, v220, s[64:65]
	global_load_dword v87, v220, s[64:65] offset:128
	v_add_u32_e32 v220, 0xa000, v186
	global_load_dword v88, v220, s[64:65]
	global_load_dword v89, v220, s[64:65] offset:128
	v_add_u32_e32 v220, 0xb000, v186
	global_load_dword v90, v220, s[64:65]
	global_load_dword v91, v220, s[64:65] offset:128
	v_add_u32_e32 v220, 0x10000, v186
	global_load_dword v92, v220, s[64:65]
	global_load_dword v93, v220, s[64:65] offset:128
	v_add_u32_e32 v220, 0x11000, v186
	global_load_dword v94, v220, s[64:65]
	global_load_dword v95, v220, s[64:65] offset:128
	v_add_u32_e32 v220, 0x12000, v186
	global_load_dword v96, v220, s[64:65]
	global_load_dword v97, v220, s[64:65] offset:128
	v_add_u32_e32 v220, 0x13000, v186
	global_load_dword v98, v220, s[64:65]
	global_load_dword v99, v220, s[64:65] offset:128
	v_add_u32_e32 v220, 0x18000, v186
	global_load_dword v100, v220, s[64:65]
	global_load_dword v101, v220, s[64:65] offset:128
	v_add_u32_e32 v220, 0x19000, v186
	global_load_dword v102, v220, s[64:65]
	global_load_dword v103, v220, s[64:65] offset:128
	v_add_u32_e32 v220, 0x1a000, v186
	global_load_dword v104, v220, s[64:65]
	global_load_dword v105, v220, s[64:65] offset:128
	v_add_u32_e32 v220, 0x1b000, v186
	global_load_dword v106, v220, s[64:65]
	global_load_dword v107, v220, s[64:65] offset:128
	v_add_u32_e32 v220, 0x20000, v186
	global_load_dword v108, v220, s[64:65]
	global_load_dword v109, v220, s[64:65] offset:128
	v_add_u32_e32 v220, 0x21000, v186
	global_load_dword v202, v220, s[64:65]
	global_load_dword v203, v220, s[64:65] offset:128
	v_add_u32_e32 v220, 0x22000, v186
	global_load_dword v204, v220, s[64:65]
	global_load_dword v205, v220, s[64:65] offset:128
	v_add_u32_e32 v220, 0x23000, v186
	global_load_dword v206, v220, s[64:65]
	global_load_dword v207, v220, s[64:65] offset:128
	v_add_u32_e32 v220, 0x28000, v186
	global_load_dword v208, v220, s[64:65]
	global_load_dword v209, v220, s[64:65] offset:128
	v_add_u32_e32 v220, 0x29000, v186
	global_load_dword v210, v220, s[64:65]
	global_load_dword v211, v220, s[64:65] offset:128
	v_add_u32_e32 v220, 0x2a000, v186
	global_load_dword v212, v220, s[64:65]
	global_load_dword v213, v220, s[64:65] offset:128
	v_add_u32_e32 v220, 0x2b000, v186
	global_load_dword v214, v220, s[64:65]
	global_load_dword v215, v220, s[64:65] offset:128
	v_add_u32_e32 v220, 0x30000, v186
	global_load_dword v216, v220, s[64:65]
	global_load_dword v217, v220, s[64:65] offset:128
	v_add_u32_e32 v220, 0x31000, v186
	global_load_dword v218, v220, s[64:65]
	global_load_dword v219, v220, s[64:65] offset:128
	v_add_u32_e32 v220, 0x32000, v186
	global_load_dword v64, v220, s[64:65]
	global_load_dword v65, v220, s[64:65] offset:128
	v_add_u32_e32 v220, 0x33000, v186
	global_load_dword v66, v220, s[64:65]
	global_load_dword v67, v220, s[64:65] offset:128
	v_add_u32_e32 v220, 0x38000, v186
	global_load_dword v68, v220, s[64:65]
	global_load_dword v69, v220, s[64:65] offset:128
	v_add_u32_e32 v220, 0x39000, v186
	global_load_dword v70, v220, s[64:65]
	global_load_dword v71, v220, s[64:65] offset:128
	v_add_u32_e32 v220, 0x3a000, v186
	global_load_dword v72, v220, s[64:65]
	global_load_dword v73, v220, s[64:65] offset:128
	v_add_u32_e32 v220, 0x3b000, v186
	global_load_dword v74, v220, s[64:65]
	global_load_dword v75, v220, s[64:65] offset:128
	s_waitcnt vmcnt(32)
; #define EPI_BEGIN(accv) EPI_BEGINM(accv, 2)
; DI void phase_ple(const Params& p, int L, char* smem) {
;     ...
;     EPI_BEGIN(acc)
;       float* xp = p.out + (size_t)row * 1024 + col;
;       float nv = *xp + gt[mt][nt][i] * v; *xp = nv; p.xb2[(size_t)row * 1024 + col] = f2bf(nv);
;     EPI_END
	v_fmac_f32_e32 v76, v110, v48
	global_store_dword v186, v76, s[64:65]
	v_cvt_pk_bf16_f32 v48, v76, v76
	global_store_short v187, v48, s[38:39]
	v_fmac_f32_e32 v77, v171, v32
	global_store_dword v186, v77, s[64:65] offset:128
	v_cvt_pk_bf16_f32 v32, v77, v77
	global_store_short v187, v32, s[38:39] offset:64
	v_add_u32_e32 v220, 0x1000, v186
	v_add_u32_e32 v221, 0x800, v187
	v_fmac_f32_e32 v78, v114, v49
	global_store_dword v220, v78, s[64:65]
	v_cvt_pk_bf16_f32 v49, v78, v78
	global_store_short v221, v49, s[38:39]
	v_fmac_f32_e32 v79, v172, v33
	global_store_dword v220, v79, s[64:65] offset:128
	v_cvt_pk_bf16_f32 v33, v79, v79
	global_store_short v221, v33, s[38:39] offset:64
	v_add_u32_e32 v220, 0x2000, v186
	v_add_u32_e32 v221, 0x1000, v187
	v_fmac_f32_e32 v80, v118, v50
	global_store_dword v220, v80, s[64:65]
	v_cvt_pk_bf16_f32 v50, v80, v80
	global_store_short v221, v50, s[38:39]
	v_fmac_f32_e32 v81, v173, v34
	global_store_dword v220, v81, s[64:65] offset:128
	v_cvt_pk_bf16_f32 v34, v81, v81
	global_store_short v221, v34, s[38:39] offset:64
	v_add_u32_e32 v220, 0x3000, v186
	v_add_u32_e32 v221, 0x1800, v187
	v_fmac_f32_e32 v82, v117, v51
	global_store_dword v220, v82, s[64:65]
	v_cvt_pk_bf16_f32 v51, v82, v82
	global_store_short v221, v51, s[38:39]
	v_fmac_f32_e32 v83, v142, v35
	global_store_dword v220, v83, s[64:65] offset:128
	v_cvt_pk_bf16_f32 v35, v83, v83
	global_store_short v221, v35, s[38:39] offset:64
	v_add_u32_e32 v220, 0x8000, v186
	v_add_u32_e32 v221, 0x4000, v187
	v_fmac_f32_e32 v84, v119, v52
	global_store_dword v220, v84, s[64:65]
	v_cvt_pk_bf16_f32 v52, v84, v84
	global_store_short v221, v52, s[38:39]
	v_fmac_f32_e32 v85, v148, v36
	global_store_dword v220, v85, s[64:65] offset:128
	v_cvt_pk_bf16_f32 v36, v85, v85
	global_store_short v221, v36, s[38:39] offset:64
	v_add_u32_e32 v220, 0x9000, v186
	v_add_u32_e32 v221, 0x4800, v187
	v_fmac_f32_e32 v86, v123, v53
	global_store_dword v220, v86, s[64:65]
	v_cvt_pk_bf16_f32 v53, v86, v86
	global_store_short v221, v53, s[38:39]
	v_fmac_f32_e32 v87, v153, v37
	global_store_dword v220, v87, s[64:65] offset:128
	v_cvt_pk_bf16_f32 v37, v87, v87
	global_store_short v221, v37, s[38:39] offset:64
	v_add_u32_e32 v220, 0xa000, v186
	v_add_u32_e32 v221, 0x5000, v187
	v_fmac_f32_e32 v88, v125, v54
	global_store_dword v220, v88, s[64:65]
	v_cvt_pk_bf16_f32 v54, v88, v88
	global_store_short v221, v54, s[38:39]
	v_fmac_f32_e32 v89, v155, v38
	global_store_dword v220, v89, s[64:65] offset:128
	v_cvt_pk_bf16_f32 v38, v89, v89
	global_store_short v221, v38, s[38:39] offset:64
	v_add_u32_e32 v220, 0xb000, v186
	v_add_u32_e32 v221, 0x5800, v187
	v_fmac_f32_e32 v90, v128, v55
	global_store_dword v220, v90, s[64:65]
	v_cvt_pk_bf16_f32 v55, v90, v90
	global_store_short v221, v55, s[38:39]
	v_fmac_f32_e32 v91, v138, v39
	global_store_dword v220, v91, s[64:65] offset:128
	v_cvt_pk_bf16_f32 v39, v91, v91
	global_store_short v221, v39, s[38:39] offset:64
	v_add_u32_e32 v220, 0x10000, v186
	v_add_u32_e32 v221, 0x8000, v187
	v_fmac_f32_e32 v92, v132, v56
	global_store_dword v220, v92, s[64:65]
	v_cvt_pk_bf16_f32 v56, v92, v92
	global_store_short v221, v56, s[38:39]
	v_fmac_f32_e32 v93, v139, v40
	global_store_dword v220, v93, s[64:65] offset:128
	v_cvt_pk_bf16_f32 v40, v93, v93
	global_store_short v221, v40, s[38:39] offset:64
	v_add_u32_e32 v220, 0x11000, v186
	v_add_u32_e32 v221, 0x8800, v187
	v_fmac_f32_e32 v94, v133, v57
	global_store_dword v220, v94, s[64:65]
	v_cvt_pk_bf16_f32 v57, v94, v94
	global_store_short v221, v57, s[38:39]
	v_fmac_f32_e32 v95, v143, v41
	global_store_dword v220, v95, s[64:65] offset:128
	v_cvt_pk_bf16_f32 v41, v95, v95
	global_store_short v221, v41, s[38:39] offset:64
	v_add_u32_e32 v220, 0x12000, v186
	v_add_u32_e32 v221, 0x9000, v187
	v_fmac_f32_e32 v96, v134, v58
	global_store_dword v220, v96, s[64:65]
	v_cvt_pk_bf16_f32 v58, v96, v96
	global_store_short v221, v58, s[38:39]
	v_fmac_f32_e32 v97, v149, v42
	global_store_dword v220, v97, s[64:65] offset:128
	v_cvt_pk_bf16_f32 v42, v97, v97
	global_store_short v221, v42, s[38:39] offset:64
	v_add_u32_e32 v220, 0x13000, v186
	v_add_u32_e32 v221, 0x9800, v187
	v_fmac_f32_e32 v98, v135, v59
	global_store_dword v220, v98, s[64:65]
	v_cvt_pk_bf16_f32 v59, v98, v98
	global_store_short v221, v59, s[38:39]
	v_fmac_f32_e32 v99, v140, v43
	global_store_dword v220, v99, s[64:65] offset:128
	v_cvt_pk_bf16_f32 v43, v99, v99
	global_store_short v221, v43, s[38:39] offset:64
	v_add_u32_e32 v220, 0x18000, v186
	v_add_u32_e32 v221, 0xc000, v187
	v_fmac_f32_e32 v100, v161, v60
	global_store_dword v220, v100, s[64:65]
	v_cvt_pk_bf16_f32 v60, v100, v100
	global_store_short v221, v60, s[38:39]
	v_fmac_f32_e32 v101, v144, v44
	global_store_dword v220, v101, s[64:65] offset:128
	v_cvt_pk_bf16_f32 v44, v101, v101
	global_store_short v221, v44, s[38:39] offset:64
	v_add_u32_e32 v220, 0x19000, v186
	v_add_u32_e32 v221, 0xc800, v187
	v_fmac_f32_e32 v102, v163, v61
	global_store_dword v220, v102, s[64:65]
	v_cvt_pk_bf16_f32 v61, v102, v102
	global_store_short v221, v61, s[38:39]
	v_fmac_f32_e32 v103, v151, v45
	global_store_dword v220, v103, s[64:65] offset:128
	v_cvt_pk_bf16_f32 v45, v103, v103
	global_store_short v221, v45, s[38:39] offset:64
	v_add_u32_e32 v220, 0x1a000, v186
	v_add_u32_e32 v221, 0xd000, v187
	v_fmac_f32_e32 v104, v165, v62
	global_store_dword v220, v104, s[64:65]
	v_cvt_pk_bf16_f32 v62, v104, v104
	global_store_short v221, v62, s[38:39]
	v_fmac_f32_e32 v105, v154, v46
	global_store_dword v220, v105, s[64:65] offset:128
	v_cvt_pk_bf16_f32 v46, v105, v105
	global_store_short v221, v46, s[38:39] offset:64
	v_add_u32_e32 v220, 0x1b000, v186
	v_add_u32_e32 v221, 0xd800, v187
	v_fmac_f32_e32 v106, v170, v63
	global_store_dword v220, v106, s[64:65]
	v_cvt_pk_bf16_f32 v63, v106, v106
	global_store_short v221, v63, s[38:39]
	v_fmac_f32_e32 v107, v145, v47
	global_store_dword v220, v107, s[64:65] offset:128
	v_cvt_pk_bf16_f32 v47, v107, v107
	global_store_short v221, v47, s[38:39] offset:64
	s_waitcnt vmcnt(63)
; #define EPI_BEGIN(accv) EPI_BEGINM(accv, 2)
; DI void phase_ple(const Params& p, int L, char* smem) {
;     ...
;   for (int id = blockIdx.x; id < 128 * 8; id += gridDim.x) {
;     ...
;     EPI_BEGIN(acc)
;       float* xp = p.out + (size_t)row * 1024 + col;
;       float nv = *xp + gt[mt][nt][i] * v; *xp = nv; p.xb2[(size_t)row * 1024 + col] = f2bf(nv);
;     EPI_END
;   }
	v_add_u32_e32 v220, 0x20000, v186
	v_add_u32_e32 v221, 0x10000, v187
	v_fmac_f32_e32 v108, v141, v16
	global_store_dword v220, v108, s[64:65]
	v_cvt_pk_bf16_f32 v16, v108, v108
	global_store_short v221, v16, s[38:39]
	v_fmac_f32_e32 v109, v178, v0
	global_store_dword v220, v109, s[64:65] offset:128
	v_cvt_pk_bf16_f32 v0, v109, v109
	global_store_short v221, v0, s[38:39] offset:64
	v_add_u32_e32 v220, 0x21000, v186
	v_add_u32_e32 v221, 0x10800, v187
	v_fmac_f32_e32 v202, v137, v17
	global_store_dword v220, v202, s[64:65]
	v_cvt_pk_bf16_f32 v17, v202, v202
	global_store_short v221, v17, s[38:39]
	v_fmac_f32_e32 v203, v179, v1
	global_store_dword v220, v203, s[64:65] offset:128
	v_cvt_pk_bf16_f32 v1, v203, v203
	global_store_short v221, v1, s[38:39] offset:64
	v_add_u32_e32 v220, 0x22000, v186
	v_add_u32_e32 v221, 0x11000, v187
	v_fmac_f32_e32 v204, v136, v18
	global_store_dword v220, v204, s[64:65]
	v_cvt_pk_bf16_f32 v18, v204, v204
	global_store_short v221, v18, s[38:39]
	v_fmac_f32_e32 v205, v180, v2
	global_store_dword v220, v205, s[64:65] offset:128
	v_cvt_pk_bf16_f32 v2, v205, v205
	global_store_short v221, v2, s[38:39] offset:64
	v_add_u32_e32 v220, 0x23000, v186
	v_add_u32_e32 v221, 0x11800, v187
	v_fmac_f32_e32 v206, v126, v19
	global_store_dword v220, v206, s[64:65]
	v_cvt_pk_bf16_f32 v19, v206, v206
	global_store_short v221, v19, s[38:39]
	v_fmac_f32_e32 v207, v146, v3
	global_store_dword v220, v207, s[64:65] offset:128
	v_cvt_pk_bf16_f32 v3, v207, v207
	global_store_short v221, v3, s[38:39] offset:64
	v_add_u32_e32 v220, 0x28000, v186
	v_add_u32_e32 v221, 0x14000, v187
	v_fmac_f32_e32 v208, v159, v20
	global_store_dword v220, v208, s[64:65]
	v_cvt_pk_bf16_f32 v20, v208, v208
	global_store_short v221, v20, s[38:39]
	v_fmac_f32_e32 v209, v147, v4
	global_store_dword v220, v209, s[64:65] offset:128
	v_cvt_pk_bf16_f32 v4, v209, v209
	global_store_short v221, v4, s[38:39] offset:64
	v_add_u32_e32 v220, 0x29000, v186
	v_add_u32_e32 v221, 0x14800, v187
	v_fmac_f32_e32 v210, v160, v21
	global_store_dword v220, v210, s[64:65]
	v_cvt_pk_bf16_f32 v21, v210, v210
	global_store_short v221, v21, s[38:39]
	v_fmac_f32_e32 v211, v150, v5
	global_store_dword v220, v211, s[64:65] offset:128
	v_cvt_pk_bf16_f32 v5, v211, v211
	global_store_short v221, v5, s[38:39] offset:64
	v_add_u32_e32 v220, 0x2a000, v186
	v_add_u32_e32 v221, 0x15000, v187
	v_fmac_f32_e32 v212, v162, v22
	global_store_dword v220, v212, s[64:65]
	v_cvt_pk_bf16_f32 v22, v212, v212
	global_store_short v221, v22, s[38:39]
	v_fmac_f32_e32 v213, v152, v6
	global_store_dword v220, v213, s[64:65] offset:128
	v_cvt_pk_bf16_f32 v6, v213, v213
	global_store_short v221, v6, s[38:39] offset:64
	v_add_u32_e32 v220, 0x2b000, v186
	v_add_u32_e32 v221, 0x15800, v187
	v_fmac_f32_e32 v214, v164, v23
	global_store_dword v220, v214, s[64:65]
	v_cvt_pk_bf16_f32 v23, v214, v214
	global_store_short v221, v23, s[38:39]
	v_fmac_f32_e32 v215, v127, v7
	global_store_dword v220, v215, s[64:65] offset:128
	v_cvt_pk_bf16_f32 v7, v215, v215
	global_store_short v221, v7, s[38:39] offset:64
	v_add_u32_e32 v220, 0x30000, v186
	v_add_u32_e32 v221, 0x18000, v187
	v_fmac_f32_e32 v216, v166, v24
	global_store_dword v220, v216, s[64:65]
	v_cvt_pk_bf16_f32 v24, v216, v216
	global_store_short v221, v24, s[38:39]
	v_fmac_f32_e32 v217, v129, v8
	global_store_dword v220, v217, s[64:65] offset:128
	v_cvt_pk_bf16_f32 v8, v217, v217
	global_store_short v221, v8, s[38:39] offset:64
	v_add_u32_e32 v220, 0x31000, v186
	v_add_u32_e32 v221, 0x18800, v187
	v_fmac_f32_e32 v218, v167, v25
	global_store_dword v220, v218, s[64:65]
	v_cvt_pk_bf16_f32 v25, v218, v218
	global_store_short v221, v25, s[38:39]
	v_fmac_f32_e32 v219, v130, v9
	global_store_dword v220, v219, s[64:65] offset:128
	v_cvt_pk_bf16_f32 v9, v219, v219
	global_store_short v221, v9, s[38:39] offset:64
	v_add_u32_e32 v220, 0x32000, v186
	v_add_u32_e32 v221, 0x19000, v187
	v_fmac_f32_e32 v64, v168, v26
	global_store_dword v220, v64, s[64:65]
	v_cvt_pk_bf16_f32 v26, v64, v64
	global_store_short v221, v26, s[38:39]
	v_fmac_f32_e32 v65, v131, v10
	global_store_dword v220, v65, s[64:65] offset:128
	v_cvt_pk_bf16_f32 v10, v65, v65
	global_store_short v221, v10, s[38:39] offset:64
	v_add_u32_e32 v220, 0x33000, v186
	v_add_u32_e32 v221, 0x19800, v187
	v_fmac_f32_e32 v66, v169, v27
	global_store_dword v220, v66, s[64:65]
	v_cvt_pk_bf16_f32 v27, v66, v66
	global_store_short v221, v27, s[38:39]
	v_fmac_f32_e32 v67, v120, v11
	global_store_dword v220, v67, s[64:65] offset:128
	v_cvt_pk_bf16_f32 v11, v67, v67
	global_store_short v221, v11, s[38:39] offset:64
	v_add_u32_e32 v220, 0x38000, v186
	v_add_u32_e32 v221, 0x1c000, v187
	v_fmac_f32_e32 v68, v174, v28
	global_store_dword v220, v68, s[64:65]
	v_cvt_pk_bf16_f32 v28, v68, v68
	global_store_short v221, v28, s[38:39]
	v_fmac_f32_e32 v69, v121, v12
	global_store_dword v220, v69, s[64:65] offset:128
	v_cvt_pk_bf16_f32 v12, v69, v69
	global_store_short v221, v12, s[38:39] offset:64
	v_add_u32_e32 v220, 0x39000, v186
	v_add_u32_e32 v221, 0x1c800, v187
	v_fmac_f32_e32 v70, v175, v29
	global_store_dword v220, v70, s[64:65]
	v_cvt_pk_bf16_f32 v29, v70, v70
	global_store_short v221, v29, s[38:39]
	v_fmac_f32_e32 v71, v122, v13
	global_store_dword v220, v71, s[64:65] offset:128
	v_cvt_pk_bf16_f32 v13, v71, v71
	global_store_short v221, v13, s[38:39] offset:64
	v_add_u32_e32 v220, 0x3a000, v186
	v_add_u32_e32 v221, 0x1d000, v187
	v_fmac_f32_e32 v72, v176, v30
	global_store_dword v220, v72, s[64:65]
	v_cvt_pk_bf16_f32 v30, v72, v72
	global_store_short v221, v30, s[38:39]
	v_fmac_f32_e32 v73, v124, v14
	global_store_dword v220, v73, s[64:65] offset:128
	v_cvt_pk_bf16_f32 v14, v73, v73
	global_store_short v221, v14, s[38:39] offset:64
	v_add_u32_e32 v220, 0x3b000, v186
	v_add_u32_e32 v221, 0x1d800, v187
	v_fmac_f32_e32 v74, v177, v31
	global_store_dword v220, v74, s[64:65]
	v_cvt_pk_bf16_f32 v31, v74, v74
	global_store_short v221, v31, s[38:39]
	v_fmac_f32_e32 v75, v116, v15
	global_store_dword v220, v75, s[64:65] offset:128
	v_cvt_pk_bf16_f32 v15, v75, v75
	global_store_short v221, v15, s[38:39] offset:64
	s_load_dword s2, s[2:3], 0x0
	s_waitcnt lgkmcnt(0)
	s_add_i32 s8, s2, s8
	s_cmpk_gt_i32 s8, 0x3ff
	s_cbranch_scc1 .LBB0_22

; DI void phase_attn1(const Params& p, int L, char* smem) {
;     ...
;   for (int it = blockIdx.x; it < 1792 + extra; it += gridDim.x) {
;     if (it < 512) attn_item<2>(p, it, smem);
;     else if (it < 1024) nsacmp_item(p, L, it - 512, smem);
;     else if (it < 1536) attn_item<0>(p, it - 1024, smem);
;     else if (it < 1792) mlaprep_item(p, L, it - 1536, smem);
;     else conv_item_C(p, L, it - 1792, smem);
;   }
.LBB0_150:
	v_readlane_b32 s2, v254, 38
	v_readlane_b32 s3, v254, 39
	s_load_dword s2, s[2:3], 0x0
	v_readlane_b32 s33, v255, 61
	s_max_i32 s3, s60, 0x800
	s_waitcnt lgkmcnt(0)
	s_add_i32 s33, s2, s33
	s_cmp_ge_i32 s33, s3
	s_cbranch_scc1 .LBB0_484
.LBB0_151:
	v_writelane_b32 v255, s33, 61
	s_lshr_b32 s2, s33, 9
	s_cmp_eq_u32 s2, 3
	s_cbranch_scc0 .Lp3_noswap
	s_xor_b32 s33, s33, 0x100
	s_cmpk_eq_i32 s60, 0x700
	s_cbranch_scc0 .Lp3_noswap
	s_cmpk_ge_i32 s33, 0x700
	s_cbranch_scc1 .LBB0_150

; DI float sigmoidf_(float v) { return 1.f / (1.f + __expf(-v)); }
; DI void phase_in(const Params& p, int L, char* smem) {
;     ...
;         EPI_BEGINM(acc, 4) p.gates[(size_t)row * 4096 + (col - 2752)] = f2bf(sigmoidf_(v)); EPI_END
.LBB0_1716:
	s_andn2_saveexec_b64 s[4:5], s[4:5]
	s_cbranch_execz .LBB0_779
	s_movk_i32 s6, 0x6b
	v_cmp_gt_u32_e32 vcc, s6, v167
	s_and_saveexec_b64 s[6:7], vcc
	s_cbranch_execz .LBB0_778
	v_add_u32_e32 v0, s34, v206
	v_or_b32_e32 v1, s33, v208
	v_lshlrev_b32_e32 v0, 13, v0
	v_add_u32_e32 v1, 0xfffff540, v1
	v_lshl_add_u32 v0, v1, 1, v0
	v_mul_f32_e32 v2, 0xbfb8aa3b, v166
	v_mul_f32_e32 v3, 0xbfb8aa3b, v151
	v_mul_f32_e32 v4, 0xbfb8aa3b, v165
	v_mul_f32_e32 v5, 0xbfb8aa3b, v150
	v_mul_f32_e32 v6, 0xbfb8aa3b, v164
	v_mul_f32_e32 v7, 0xbfb8aa3b, v149
	v_mul_f32_e32 v8, 0xbfb8aa3b, v163
	v_mul_f32_e32 v9, 0xbfb8aa3b, v148
	v_exp_f32_e32 v2, v2
	v_exp_f32_e32 v3, v3
	v_exp_f32_e32 v4, v4
	v_exp_f32_e32 v5, v5
	v_exp_f32_e32 v6, v6
	v_exp_f32_e32 v7, v7
	v_exp_f32_e32 v8, v8
	v_exp_f32_e32 v9, v9
	v_add_f32_e32 v2, 1.0, v2
	v_add_f32_e32 v3, 1.0, v3
	v_add_f32_e32 v4, 1.0, v4
	v_add_f32_e32 v5, 1.0, v5
	v_add_f32_e32 v6, 1.0, v6
	v_add_f32_e32 v7, 1.0, v7
	v_add_f32_e32 v8, 1.0, v8
	v_add_f32_e32 v9, 1.0, v9
	v_min_f32_e32 v2, 0x7f7fffff, v2
	v_min_f32_e32 v3, 0x7f7fffff, v3
	v_min_f32_e32 v4, 0x7f7fffff, v4
	v_min_f32_e32 v5, 0x7f7fffff, v5
	v_min_f32_e32 v6, 0x7f7fffff, v6
	v_min_f32_e32 v7, 0x7f7fffff, v7
	v_min_f32_e32 v8, 0x7f7fffff, v8
	v_min_f32_e32 v9, 0x7f7fffff, v9
	v_rcp_f32_e32 v10, v2
	v_rcp_f32_e32 v11, v3
	v_rcp_f32_e32 v12, v4
	v_rcp_f32_e32 v13, v5
	v_rcp_f32_e32 v14, v6
	v_rcp_f32_e32 v15, v7
	v_rcp_f32_e32 v16, v8
	v_rcp_f32_e32 v17, v9
	v_fma_f32 v18, -v2, v10, 1.0
	v_fma_f32 v19, -v3, v11, 1.0
	v_fma_f32 v20, -v4, v12, 1.0
	v_fma_f32 v21, -v5, v13, 1.0
	v_fma_f32 v22, -v6, v14, 1.0
	v_fma_f32 v23, -v7, v15, 1.0
	v_fma_f32 v24, -v8, v16, 1.0
	v_fma_f32 v25, -v9, v17, 1.0
	v_fmac_f32_e32 v10, v18, v10
	v_fmac_f32_e32 v11, v19, v11
	v_fmac_f32_e32 v12, v20, v12
	v_fmac_f32_e32 v13, v21, v13
	v_fmac_f32_e32 v14, v22, v14
	v_fmac_f32_e32 v15, v23, v15
	v_fmac_f32_e32 v16, v24, v16
	v_fmac_f32_e32 v17, v25, v17
	v_cvt_pk_bf16_f32 v10, v10, v10
	v_cvt_pk_bf16_f32 v11, v11, v11
	v_cvt_pk_bf16_f32 v12, v12, v12
	v_cvt_pk_bf16_f32 v13, v13, v13
	v_cvt_pk_bf16_f32 v14, v14, v14
	v_cvt_pk_bf16_f32 v15, v15, v15
	v_cvt_pk_bf16_f32 v16, v16, v16
	v_cvt_pk_bf16_f32 v17, v17, v17
	global_store_short v0, v10, s[70:71]
	global_store_short v0, v11, s[70:71] offset:64
	v_add_u32_e32 v26, 0x2000, v0
	global_store_short v26, v12, s[70:71]
	global_store_short v26, v13, s[70:71] offset:64
	v_add_u32_e32 v26, 0x4000, v0
	global_store_short v26, v14, s[70:71]
	global_store_short v26, v15, s[70:71] offset:64
	v_add_u32_e32 v26, 0x6000, v0
	global_store_short v26, v16, s[70:71]
	global_store_short v26, v17, s[70:71] offset:64
	v_mul_f32_e32 v2, 0xbfb8aa3b, v162
	v_mul_f32_e32 v3, 0xbfb8aa3b, v147
	v_mul_f32_e32 v4, 0xbfb8aa3b, v161
	v_mul_f32_e32 v5, 0xbfb8aa3b, v146
	v_mul_f32_e32 v6, 0xbfb8aa3b, v160
	v_mul_f32_e32 v7, 0xbfb8aa3b, v145
	v_mul_f32_e32 v8, 0xbfb8aa3b, v159
	v_mul_f32_e32 v9, 0xbfb8aa3b, v144
	v_exp_f32_e32 v2, v2
	v_exp_f32_e32 v3, v3
	v_exp_f32_e32 v4, v4
	v_exp_f32_e32 v5, v5
	v_exp_f32_e32 v6, v6
	v_exp_f32_e32 v7, v7
	v_exp_f32_e32 v8, v8
	v_exp_f32_e32 v9, v9
	v_add_f32_e32 v2, 1.0, v2
	v_add_f32_e32 v3, 1.0, v3
	v_add_f32_e32 v4, 1.0, v4
	v_add_f32_e32 v5, 1.0, v5
	v_add_f32_e32 v6, 1.0, v6
	v_add_f32_e32 v7, 1.0, v7
	v_add_f32_e32 v8, 1.0, v8
	v_add_f32_e32 v9, 1.0, v9
	v_min_f32_e32 v2, 0x7f7fffff, v2
	v_min_f32_e32 v3, 0x7f7fffff, v3
	v_min_f32_e32 v4, 0x7f7fffff, v4
	v_min_f32_e32 v5, 0x7f7fffff, v5
	v_min_f32_e32 v6, 0x7f7fffff, v6
	v_min_f32_e32 v7, 0x7f7fffff, v7
	v_min_f32_e32 v8, 0x7f7fffff, v8
	v_min_f32_e32 v9, 0x7f7fffff, v9
	v_rcp_f32_e32 v10, v2
	v_rcp_f32_e32 v11, v3
	v_rcp_f32_e32 v12, v4
	v_rcp_f32_e32 v13, v5
	v_rcp_f32_e32 v14, v6
	v_rcp_f32_e32 v15, v7
	v_rcp_f32_e32 v16, v8
	v_rcp_f32_e32 v17, v9
	v_fma_f32 v18, -v2, v10, 1.0
	v_fma_f32 v19, -v3, v11, 1.0
	v_fma_f32 v20, -v4, v12, 1.0
	v_fma_f32 v21, -v5, v13, 1.0
	v_fma_f32 v22, -v6, v14, 1.0
	v_fma_f32 v23, -v7, v15, 1.0
	v_fma_f32 v24, -v8, v16, 1.0
	v_fma_f32 v25, -v9, v17, 1.0
	v_fmac_f32_e32 v10, v18, v10
	v_fmac_f32_e32 v11, v19, v11
	v_fmac_f32_e32 v12, v20, v12
	v_fmac_f32_e32 v13, v21, v13
	v_fmac_f32_e32 v14, v22, v14
	v_fmac_f32_e32 v15, v23, v15
	v_fmac_f32_e32 v16, v24, v16
	v_fmac_f32_e32 v17, v25, v17
	v_cvt_pk_bf16_f32 v10, v10, v10
	v_cvt_pk_bf16_f32 v11, v11, v11
	v_cvt_pk_bf16_f32 v12, v12, v12
	v_cvt_pk_bf16_f32 v13, v13, v13
	v_cvt_pk_bf16_f32 v14, v14, v14
	v_cvt_pk_bf16_f32 v15, v15, v15
	v_cvt_pk_bf16_f32 v16, v16, v16
	v_cvt_pk_bf16_f32 v17, v17, v17
	v_add_u32_e32 v26, 0x10000, v0
	global_store_short v26, v10, s[70:71]
	global_store_short v26, v11, s[70:71] offset:64
	v_add_u32_e32 v26, 0x12000, v0
	global_store_short v26, v12, s[70:71]
	global_store_short v26, v13, s[70:71] offset:64
	v_add_u32_e32 v26, 0x14000, v0
	global_store_short v26, v14, s[70:71]
	global_store_short v26, v15, s[70:71] offset:64
	v_add_u32_e32 v26, 0x16000, v0
	global_store_short v26, v16, s[70:71]
	global_store_short v26, v17, s[70:71] offset:64
	v_mul_f32_e32 v2, 0xbfb8aa3b, v158
	v_mul_f32_e32 v3, 0xbfb8aa3b, v143
	v_mul_f32_e32 v4, 0xbfb8aa3b, v157
	v_mul_f32_e32 v5, 0xbfb8aa3b, v142
	v_mul_f32_e32 v6, 0xbfb8aa3b, v156
	v_mul_f32_e32 v7, 0xbfb8aa3b, v141
	v_mul_f32_e32 v8, 0xbfb8aa3b, v155
	v_mul_f32_e32 v9, 0xbfb8aa3b, v140
	v_exp_f32_e32 v2, v2
	v_exp_f32_e32 v3, v3
	v_exp_f32_e32 v4, v4
	v_exp_f32_e32 v5, v5
	v_exp_f32_e32 v6, v6
	v_exp_f32_e32 v7, v7
	v_exp_f32_e32 v8, v8
	v_exp_f32_e32 v9, v9
	v_add_f32_e32 v2, 1.0, v2
	v_add_f32_e32 v3, 1.0, v3
	v_add_f32_e32 v4, 1.0, v4
	v_add_f32_e32 v5, 1.0, v5
	v_add_f32_e32 v6, 1.0, v6
	v_add_f32_e32 v7, 1.0, v7
; DI float sigmoidf_(float v) { return 1.f / (1.f + __expf(-v)); }
; DI void phase_in(const Params& p, int L, char* smem) {
;     ...
;         EPI_BEGINM(acc, 4) p.gates[(size_t)row * 4096 + (col - 2752)] = f2bf(sigmoidf_(v)); EPI_END
	v_add_f32_e32 v8, 1.0, v8
	v_add_f32_e32 v9, 1.0, v9
	v_min_f32_e32 v2, 0x7f7fffff, v2
	v_min_f32_e32 v3, 0x7f7fffff, v3
	v_min_f32_e32 v4, 0x7f7fffff, v4
	v_min_f32_e32 v5, 0x7f7fffff, v5
	v_min_f32_e32 v6, 0x7f7fffff, v6
	v_min_f32_e32 v7, 0x7f7fffff, v7
	v_min_f32_e32 v8, 0x7f7fffff, v8
	v_min_f32_e32 v9, 0x7f7fffff, v9
	v_rcp_f32_e32 v10, v2
	v_rcp_f32_e32 v11, v3
	v_rcp_f32_e32 v12, v4
	v_rcp_f32_e32 v13, v5
	v_rcp_f32_e32 v14, v6
	v_rcp_f32_e32 v15, v7
	v_rcp_f32_e32 v16, v8
	v_rcp_f32_e32 v17, v9
	v_fma_f32 v18, -v2, v10, 1.0
	v_fma_f32 v19, -v3, v11, 1.0
	v_fma_f32 v20, -v4, v12, 1.0
	v_fma_f32 v21, -v5, v13, 1.0
	v_fma_f32 v22, -v6, v14, 1.0
	v_fma_f32 v23, -v7, v15, 1.0
	v_fma_f32 v24, -v8, v16, 1.0
	v_fma_f32 v25, -v9, v17, 1.0
	v_fmac_f32_e32 v10, v18, v10
	v_fmac_f32_e32 v11, v19, v11
	v_fmac_f32_e32 v12, v20, v12
	v_fmac_f32_e32 v13, v21, v13
	v_fmac_f32_e32 v14, v22, v14
	v_fmac_f32_e32 v15, v23, v15
	v_fmac_f32_e32 v16, v24, v16
	v_fmac_f32_e32 v17, v25, v17
	v_cvt_pk_bf16_f32 v10, v10, v10
	v_cvt_pk_bf16_f32 v11, v11, v11
	v_cvt_pk_bf16_f32 v12, v12, v12
	v_cvt_pk_bf16_f32 v13, v13, v13
	v_cvt_pk_bf16_f32 v14, v14, v14
	v_cvt_pk_bf16_f32 v15, v15, v15
	v_cvt_pk_bf16_f32 v16, v16, v16
	v_cvt_pk_bf16_f32 v17, v17, v17
	v_add_u32_e32 v26, 0x20000, v0
	global_store_short v26, v10, s[70:71]
	global_store_short v26, v11, s[70:71] offset:64
	v_add_u32_e32 v26, 0x22000, v0
	global_store_short v26, v12, s[70:71]
	global_store_short v26, v13, s[70:71] offset:64
	v_add_u32_e32 v26, 0x24000, v0
	global_store_short v26, v14, s[70:71]
	global_store_short v26, v15, s[70:71] offset:64
	v_add_u32_e32 v26, 0x26000, v0
	global_store_short v26, v16, s[70:71]
	global_store_short v26, v17, s[70:71] offset:64
	v_mul_f32_e32 v2, 0xbfb8aa3b, v154
	v_mul_f32_e32 v3, 0xbfb8aa3b, v139
	v_mul_f32_e32 v4, 0xbfb8aa3b, v153
	v_mul_f32_e32 v5, 0xbfb8aa3b, v138
	v_mul_f32_e32 v6, 0xbfb8aa3b, v152
	v_mul_f32_e32 v7, 0xbfb8aa3b, v137
	v_mul_f32_e32 v8, 0xbfb8aa3b, v103
	v_mul_f32_e32 v9, 0xbfb8aa3b, v136
	v_exp_f32_e32 v2, v2
	v_exp_f32_e32 v3, v3
	v_exp_f32_e32 v4, v4
	v_exp_f32_e32 v5, v5
	v_exp_f32_e32 v6, v6
	v_exp_f32_e32 v7, v7
	v_exp_f32_e32 v8, v8
	v_exp_f32_e32 v9, v9
	v_add_f32_e32 v2, 1.0, v2
	v_add_f32_e32 v3, 1.0, v3
	v_add_f32_e32 v4, 1.0, v4
	v_add_f32_e32 v5, 1.0, v5
	v_add_f32_e32 v6, 1.0, v6
	v_add_f32_e32 v7, 1.0, v7
	v_add_f32_e32 v8, 1.0, v8
	v_add_f32_e32 v9, 1.0, v9
	v_min_f32_e32 v2, 0x7f7fffff, v2
	v_min_f32_e32 v3, 0x7f7fffff, v3
	v_min_f32_e32 v4, 0x7f7fffff, v4
	v_min_f32_e32 v5, 0x7f7fffff, v5
	v_min_f32_e32 v6, 0x7f7fffff, v6
	v_min_f32_e32 v7, 0x7f7fffff, v7
	v_min_f32_e32 v8, 0x7f7fffff, v8
	v_min_f32_e32 v9, 0x7f7fffff, v9
	v_rcp_f32_e32 v10, v2
	v_rcp_f32_e32 v11, v3
	v_rcp_f32_e32 v12, v4
	v_rcp_f32_e32 v13, v5
	v_rcp_f32_e32 v14, v6
	v_rcp_f32_e32 v15, v7
	v_rcp_f32_e32 v16, v8
	v_rcp_f32_e32 v17, v9
	v_fma_f32 v18, -v2, v10, 1.0
	v_fma_f32 v19, -v3, v11, 1.0
	v_fma_f32 v20, -v4, v12, 1.0
	v_fma_f32 v21, -v5, v13, 1.0
	v_fma_f32 v22, -v6, v14, 1.0
	v_fma_f32 v23, -v7, v15, 1.0
	v_fma_f32 v24, -v8, v16, 1.0
	v_fma_f32 v25, -v9, v17, 1.0
	v_fmac_f32_e32 v10, v18, v10
	v_fmac_f32_e32 v11, v19, v11
	v_fmac_f32_e32 v12, v20, v12
	v_fmac_f32_e32 v13, v21, v13
	v_fmac_f32_e32 v14, v22, v14
	v_fmac_f32_e32 v15, v23, v15
	v_fmac_f32_e32 v16, v24, v16
	v_fmac_f32_e32 v17, v25, v17
	v_cvt_pk_bf16_f32 v10, v10, v10
	v_cvt_pk_bf16_f32 v11, v11, v11
	v_cvt_pk_bf16_f32 v12, v12, v12
	v_cvt_pk_bf16_f32 v13, v13, v13
	v_cvt_pk_bf16_f32 v14, v14, v14
	v_cvt_pk_bf16_f32 v15, v15, v15
	v_cvt_pk_bf16_f32 v16, v16, v16
	v_cvt_pk_bf16_f32 v17, v17, v17
	v_add_u32_e32 v26, 0x30000, v0
	global_store_short v26, v10, s[70:71]
	global_store_short v26, v11, s[70:71] offset:64
	v_add_u32_e32 v26, 0x32000, v0
	global_store_short v26, v12, s[70:71]
	global_store_short v26, v13, s[70:71] offset:64
	v_add_u32_e32 v26, 0x34000, v0
	global_store_short v26, v14, s[70:71]
	global_store_short v26, v15, s[70:71] offset:64
	v_add_u32_e32 v26, 0x36000, v0
	global_store_short v26, v16, s[70:71]
	global_store_short v26, v17, s[70:71] offset:64
	v_mul_f32_e32 v2, 0xbfb8aa3b, v135
	v_mul_f32_e32 v3, 0xbfb8aa3b, v119
	v_mul_f32_e32 v4, 0xbfb8aa3b, v134
	v_mul_f32_e32 v5, 0xbfb8aa3b, v118
	v_mul_f32_e32 v6, 0xbfb8aa3b, v133
	v_mul_f32_e32 v7, 0xbfb8aa3b, v117
	v_mul_f32_e32 v8, 0xbfb8aa3b, v132
	v_mul_f32_e32 v9, 0xbfb8aa3b, v116
	v_exp_f32_e32 v2, v2
	v_exp_f32_e32 v3, v3
	v_exp_f32_e32 v4, v4
	v_exp_f32_e32 v5, v5
	v_exp_f32_e32 v6, v6
	v_exp_f32_e32 v7, v7
	v_exp_f32_e32 v8, v8
	v_exp_f32_e32 v9, v9
	v_add_f32_e32 v2, 1.0, v2
	v_add_f32_e32 v3, 1.0, v3
	v_add_f32_e32 v4, 1.0, v4
	v_add_f32_e32 v5, 1.0, v5
	v_add_f32_e32 v6, 1.0, v6
	v_add_f32_e32 v7, 1.0, v7
	v_add_f32_e32 v8, 1.0, v8
	v_add_f32_e32 v9, 1.0, v9
	v_min_f32_e32 v2, 0x7f7fffff, v2
	v_min_f32_e32 v3, 0x7f7fffff, v3
	v_min_f32_e32 v4, 0x7f7fffff, v4
	v_min_f32_e32 v5, 0x7f7fffff, v5
	v_min_f32_e32 v6, 0x7f7fffff, v6
	v_min_f32_e32 v7, 0x7f7fffff, v7
	v_min_f32_e32 v8, 0x7f7fffff, v8
	v_min_f32_e32 v9, 0x7f7fffff, v9
	v_rcp_f32_e32 v10, v2
	v_rcp_f32_e32 v11, v3
	v_rcp_f32_e32 v12, v4
	v_rcp_f32_e32 v13, v5
	v_rcp_f32_e32 v14, v6
	v_rcp_f32_e32 v15, v7
	v_rcp_f32_e32 v16, v8
	v_rcp_f32_e32 v17, v9
	v_fma_f32 v18, -v2, v10, 1.0
	v_fma_f32 v19, -v3, v11, 1.0
	v_fma_f32 v20, -v4, v12, 1.0
	v_fma_f32 v21, -v5, v13, 1.0
	v_fma_f32 v22, -v6, v14, 1.0
	v_fma_f32 v23, -v7, v15, 1.0
	v_fma_f32 v24, -v8, v16, 1.0
	v_fma_f32 v25, -v9, v17, 1.0
	v_fmac_f32_e32 v10, v18, v10
	v_fmac_f32_e32 v11, v19, v11
	v_fmac_f32_e32 v12, v20, v12
	v_fmac_f32_e32 v13, v21, v13
	v_fmac_f32_e32 v14, v22, v14
	v_fmac_f32_e32 v15, v23, v15
; DI float sigmoidf_(float v) { return 1.f / (1.f + __expf(-v)); }
; DI void phase_in(const Params& p, int L, char* smem) {
;     ...
;         EPI_BEGINM(acc, 4) p.gates[(size_t)row * 4096 + (col - 2752)] = f2bf(sigmoidf_(v)); EPI_END
	v_fmac_f32_e32 v16, v24, v16
	v_fmac_f32_e32 v17, v25, v17
	v_cvt_pk_bf16_f32 v10, v10, v10
	v_cvt_pk_bf16_f32 v11, v11, v11
	v_cvt_pk_bf16_f32 v12, v12, v12
	v_cvt_pk_bf16_f32 v13, v13, v13
	v_cvt_pk_bf16_f32 v14, v14, v14
	v_cvt_pk_bf16_f32 v15, v15, v15
	v_cvt_pk_bf16_f32 v16, v16, v16
	v_cvt_pk_bf16_f32 v17, v17, v17
	v_add_u32_e32 v26, 0x40000, v0
	global_store_short v26, v10, s[70:71]
	global_store_short v26, v11, s[70:71] offset:64
	v_add_u32_e32 v26, 0x42000, v0
	global_store_short v26, v12, s[70:71]
	global_store_short v26, v13, s[70:71] offset:64
	v_add_u32_e32 v26, 0x44000, v0
	global_store_short v26, v14, s[70:71]
	global_store_short v26, v15, s[70:71] offset:64
	v_add_u32_e32 v26, 0x46000, v0
	global_store_short v26, v16, s[70:71]
	global_store_short v26, v17, s[70:71] offset:64
	v_mul_f32_e32 v2, 0xbfb8aa3b, v131
	v_mul_f32_e32 v3, 0xbfb8aa3b, v115
	v_mul_f32_e32 v4, 0xbfb8aa3b, v130
	v_mul_f32_e32 v5, 0xbfb8aa3b, v114
	v_mul_f32_e32 v6, 0xbfb8aa3b, v129
	v_mul_f32_e32 v7, 0xbfb8aa3b, v113
	v_mul_f32_e32 v8, 0xbfb8aa3b, v128
	v_mul_f32_e32 v9, 0xbfb8aa3b, v112
	v_exp_f32_e32 v2, v2
	v_exp_f32_e32 v3, v3
	v_exp_f32_e32 v4, v4
	v_exp_f32_e32 v5, v5
	v_exp_f32_e32 v6, v6
	v_exp_f32_e32 v7, v7
	v_exp_f32_e32 v8, v8
	v_exp_f32_e32 v9, v9
	v_add_f32_e32 v2, 1.0, v2
	v_add_f32_e32 v3, 1.0, v3
	v_add_f32_e32 v4, 1.0, v4
	v_add_f32_e32 v5, 1.0, v5
	v_add_f32_e32 v6, 1.0, v6
	v_add_f32_e32 v7, 1.0, v7
	v_add_f32_e32 v8, 1.0, v8
	v_add_f32_e32 v9, 1.0, v9
	v_min_f32_e32 v2, 0x7f7fffff, v2
	v_min_f32_e32 v3, 0x7f7fffff, v3
	v_min_f32_e32 v4, 0x7f7fffff, v4
	v_min_f32_e32 v5, 0x7f7fffff, v5
	v_min_f32_e32 v6, 0x7f7fffff, v6
	v_min_f32_e32 v7, 0x7f7fffff, v7
	v_min_f32_e32 v8, 0x7f7fffff, v8
	v_min_f32_e32 v9, 0x7f7fffff, v9
	v_rcp_f32_e32 v10, v2
	v_rcp_f32_e32 v11, v3
	v_rcp_f32_e32 v12, v4
	v_rcp_f32_e32 v13, v5
	v_rcp_f32_e32 v14, v6
	v_rcp_f32_e32 v15, v7
	v_rcp_f32_e32 v16, v8
	v_rcp_f32_e32 v17, v9
	v_fma_f32 v18, -v2, v10, 1.0
	v_fma_f32 v19, -v3, v11, 1.0
	v_fma_f32 v20, -v4, v12, 1.0
	v_fma_f32 v21, -v5, v13, 1.0
	v_fma_f32 v22, -v6, v14, 1.0
	v_fma_f32 v23, -v7, v15, 1.0
	v_fma_f32 v24, -v8, v16, 1.0
	v_fma_f32 v25, -v9, v17, 1.0
	v_fmac_f32_e32 v10, v18, v10
	v_fmac_f32_e32 v11, v19, v11
	v_fmac_f32_e32 v12, v20, v12
	v_fmac_f32_e32 v13, v21, v13
	v_fmac_f32_e32 v14, v22, v14
	v_fmac_f32_e32 v15, v23, v15
	v_fmac_f32_e32 v16, v24, v16
	v_fmac_f32_e32 v17, v25, v17
	v_cvt_pk_bf16_f32 v10, v10, v10
	v_cvt_pk_bf16_f32 v11, v11, v11
	v_cvt_pk_bf16_f32 v12, v12, v12
	v_cvt_pk_bf16_f32 v13, v13, v13
	v_cvt_pk_bf16_f32 v14, v14, v14
	v_cvt_pk_bf16_f32 v15, v15, v15
	v_cvt_pk_bf16_f32 v16, v16, v16
	v_cvt_pk_bf16_f32 v17, v17, v17
	v_add_u32_e32 v26, 0x50000, v0
	global_store_short v26, v10, s[70:71]
	global_store_short v26, v11, s[70:71] offset:64
	v_add_u32_e32 v26, 0x52000, v0
	global_store_short v26, v12, s[70:71]
	global_store_short v26, v13, s[70:71] offset:64
	v_add_u32_e32 v26, 0x54000, v0
	global_store_short v26, v14, s[70:71]
	global_store_short v26, v15, s[70:71] offset:64
	v_add_u32_e32 v26, 0x56000, v0
	global_store_short v26, v16, s[70:71]
	global_store_short v26, v17, s[70:71] offset:64
	v_mul_f32_e32 v2, 0xbfb8aa3b, v127
	v_mul_f32_e32 v3, 0xbfb8aa3b, v111
	v_mul_f32_e32 v4, 0xbfb8aa3b, v126
	v_mul_f32_e32 v5, 0xbfb8aa3b, v110
	v_mul_f32_e32 v6, 0xbfb8aa3b, v125
	v_mul_f32_e32 v7, 0xbfb8aa3b, v109
	v_mul_f32_e32 v8, 0xbfb8aa3b, v124
	v_mul_f32_e32 v9, 0xbfb8aa3b, v108
	v_exp_f32_e32 v2, v2
	v_exp_f32_e32 v3, v3
	v_exp_f32_e32 v4, v4
	v_exp_f32_e32 v5, v5
	v_exp_f32_e32 v6, v6
	v_exp_f32_e32 v7, v7
	v_exp_f32_e32 v8, v8
	v_exp_f32_e32 v9, v9
	v_add_f32_e32 v2, 1.0, v2
	v_add_f32_e32 v3, 1.0, v3
	v_add_f32_e32 v4, 1.0, v4
	v_add_f32_e32 v5, 1.0, v5
	v_add_f32_e32 v6, 1.0, v6
	v_add_f32_e32 v7, 1.0, v7
	v_add_f32_e32 v8, 1.0, v8
	v_add_f32_e32 v9, 1.0, v9
	v_min_f32_e32 v2, 0x7f7fffff, v2
	v_min_f32_e32 v3, 0x7f7fffff, v3
	v_min_f32_e32 v4, 0x7f7fffff, v4
	v_min_f32_e32 v5, 0x7f7fffff, v5
	v_min_f32_e32 v6, 0x7f7fffff, v6
	v_min_f32_e32 v7, 0x7f7fffff, v7
	v_min_f32_e32 v8, 0x7f7fffff, v8
	v_min_f32_e32 v9, 0x7f7fffff, v9
	v_rcp_f32_e32 v10, v2
	v_rcp_f32_e32 v11, v3
	v_rcp_f32_e32 v12, v4
	v_rcp_f32_e32 v13, v5
	v_rcp_f32_e32 v14, v6
	v_rcp_f32_e32 v15, v7
	v_rcp_f32_e32 v16, v8
	v_rcp_f32_e32 v17, v9
	v_fma_f32 v18, -v2, v10, 1.0
	v_fma_f32 v19, -v3, v11, 1.0
	v_fma_f32 v20, -v4, v12, 1.0
	v_fma_f32 v21, -v5, v13, 1.0
	v_fma_f32 v22, -v6, v14, 1.0
	v_fma_f32 v23, -v7, v15, 1.0
	v_fma_f32 v24, -v8, v16, 1.0
	v_fma_f32 v25, -v9, v17, 1.0
	v_fmac_f32_e32 v10, v18, v10
	v_fmac_f32_e32 v11, v19, v11
	v_fmac_f32_e32 v12, v20, v12
	v_fmac_f32_e32 v13, v21, v13
	v_fmac_f32_e32 v14, v22, v14
	v_fmac_f32_e32 v15, v23, v15
	v_fmac_f32_e32 v16, v24, v16
	v_fmac_f32_e32 v17, v25, v17
	v_cvt_pk_bf16_f32 v10, v10, v10
	v_cvt_pk_bf16_f32 v11, v11, v11
	v_cvt_pk_bf16_f32 v12, v12, v12
	v_cvt_pk_bf16_f32 v13, v13, v13
	v_cvt_pk_bf16_f32 v14, v14, v14
	v_cvt_pk_bf16_f32 v15, v15, v15
	v_cvt_pk_bf16_f32 v16, v16, v16
	v_cvt_pk_bf16_f32 v17, v17, v17
	v_add_u32_e32 v26, 0x60000, v0
	global_store_short v26, v10, s[70:71]
	global_store_short v26, v11, s[70:71] offset:64
	v_add_u32_e32 v26, 0x62000, v0
	global_store_short v26, v12, s[70:71]
	global_store_short v26, v13, s[70:71] offset:64
	v_add_u32_e32 v26, 0x64000, v0
	global_store_short v26, v14, s[70:71]
	global_store_short v26, v15, s[70:71] offset:64
	v_add_u32_e32 v26, 0x66000, v0
	global_store_short v26, v16, s[70:71]
	global_store_short v26, v17, s[70:71] offset:64
	v_mul_f32_e32 v2, 0xbfb8aa3b, v123
	v_mul_f32_e32 v3, 0xbfb8aa3b, v107
	v_mul_f32_e32 v4, 0xbfb8aa3b, v122
; DI float sigmoidf_(float v) { return 1.f / (1.f + __expf(-v)); }
; DI void phase_in(const Params& p, int L, char* smem) {
;     ...
;         EPI_BEGINM(acc, 4) p.gates[(size_t)row * 4096 + (col - 2752)] = f2bf(sigmoidf_(v)); EPI_END
	v_mul_f32_e32 v5, 0xbfb8aa3b, v106
	v_mul_f32_e32 v6, 0xbfb8aa3b, v121
	v_mul_f32_e32 v7, 0xbfb8aa3b, v105
	v_mul_f32_e32 v8, 0xbfb8aa3b, v120
	v_mul_f32_e32 v9, 0xbfb8aa3b, v104
	v_exp_f32_e32 v2, v2
	v_exp_f32_e32 v3, v3
	v_exp_f32_e32 v4, v4
	v_exp_f32_e32 v5, v5
	v_exp_f32_e32 v6, v6
	v_exp_f32_e32 v7, v7
	v_exp_f32_e32 v8, v8
	v_exp_f32_e32 v9, v9
	v_add_f32_e32 v2, 1.0, v2
	v_add_f32_e32 v3, 1.0, v3
	v_add_f32_e32 v4, 1.0, v4
	v_add_f32_e32 v5, 1.0, v5
	v_add_f32_e32 v6, 1.0, v6
	v_add_f32_e32 v7, 1.0, v7
	v_add_f32_e32 v8, 1.0, v8
	v_add_f32_e32 v9, 1.0, v9
	v_min_f32_e32 v2, 0x7f7fffff, v2
	v_min_f32_e32 v3, 0x7f7fffff, v3
	v_min_f32_e32 v4, 0x7f7fffff, v4
	v_min_f32_e32 v5, 0x7f7fffff, v5
	v_min_f32_e32 v6, 0x7f7fffff, v6
	v_min_f32_e32 v7, 0x7f7fffff, v7
	v_min_f32_e32 v8, 0x7f7fffff, v8
	v_min_f32_e32 v9, 0x7f7fffff, v9
	v_rcp_f32_e32 v10, v2
	v_rcp_f32_e32 v11, v3
	v_rcp_f32_e32 v12, v4
	v_rcp_f32_e32 v13, v5
	v_rcp_f32_e32 v14, v6
	v_rcp_f32_e32 v15, v7
	v_rcp_f32_e32 v16, v8
	v_rcp_f32_e32 v17, v9
	v_fma_f32 v18, -v2, v10, 1.0
	v_fma_f32 v19, -v3, v11, 1.0
	v_fma_f32 v20, -v4, v12, 1.0
	v_fma_f32 v21, -v5, v13, 1.0
	v_fma_f32 v22, -v6, v14, 1.0
	v_fma_f32 v23, -v7, v15, 1.0
	v_fma_f32 v24, -v8, v16, 1.0
	v_fma_f32 v25, -v9, v17, 1.0
	v_fmac_f32_e32 v10, v18, v10
	v_fmac_f32_e32 v11, v19, v11
	v_fmac_f32_e32 v12, v20, v12
	v_fmac_f32_e32 v13, v21, v13
	v_fmac_f32_e32 v14, v22, v14
	v_fmac_f32_e32 v15, v23, v15
	v_fmac_f32_e32 v16, v24, v16
	v_fmac_f32_e32 v17, v25, v17
	v_cvt_pk_bf16_f32 v10, v10, v10
	v_cvt_pk_bf16_f32 v11, v11, v11
	v_cvt_pk_bf16_f32 v12, v12, v12
	v_cvt_pk_bf16_f32 v13, v13, v13
	v_cvt_pk_bf16_f32 v14, v14, v14
	v_cvt_pk_bf16_f32 v15, v15, v15
	v_cvt_pk_bf16_f32 v16, v16, v16
	v_cvt_pk_bf16_f32 v17, v17, v17
	v_add_u32_e32 v26, 0x70000, v0
	global_store_short v26, v10, s[70:71]
	global_store_short v26, v11, s[70:71] offset:64
	v_add_u32_e32 v26, 0x72000, v0
	global_store_short v26, v12, s[70:71]
	global_store_short v26, v13, s[70:71] offset:64
	v_add_u32_e32 v26, 0x74000, v0
	global_store_short v26, v14, s[70:71]
	global_store_short v26, v15, s[70:71] offset:64
	v_add_u32_e32 v26, 0x76000, v0
	global_store_short v26, v16, s[70:71]
	global_store_short v26, v17, s[70:71] offset:64
	v_mul_f32_e32 v2, 0xbfb8aa3b, v102
	v_mul_f32_e32 v3, 0xbfb8aa3b, v85
	v_mul_f32_e32 v4, 0xbfb8aa3b, v101
	v_mul_f32_e32 v5, 0xbfb8aa3b, v84
	v_mul_f32_e32 v6, 0xbfb8aa3b, v100
	v_mul_f32_e32 v7, 0xbfb8aa3b, v83
	v_mul_f32_e32 v8, 0xbfb8aa3b, v98
	v_mul_f32_e32 v9, 0xbfb8aa3b, v82
	v_exp_f32_e32 v2, v2
	v_exp_f32_e32 v3, v3
	v_exp_f32_e32 v4, v4
	v_exp_f32_e32 v5, v5
	v_exp_f32_e32 v6, v6
	v_exp_f32_e32 v7, v7
	v_exp_f32_e32 v8, v8
	v_exp_f32_e32 v9, v9
	v_add_f32_e32 v2, 1.0, v2
	v_add_f32_e32 v3, 1.0, v3
	v_add_f32_e32 v4, 1.0, v4
	v_add_f32_e32 v5, 1.0, v5
	v_add_f32_e32 v6, 1.0, v6
	v_add_f32_e32 v7, 1.0, v7
	v_add_f32_e32 v8, 1.0, v8
	v_add_f32_e32 v9, 1.0, v9
	v_min_f32_e32 v2, 0x7f7fffff, v2
	v_min_f32_e32 v3, 0x7f7fffff, v3
	v_min_f32_e32 v4, 0x7f7fffff, v4
	v_min_f32_e32 v5, 0x7f7fffff, v5
	v_min_f32_e32 v6, 0x7f7fffff, v6
	v_min_f32_e32 v7, 0x7f7fffff, v7
	v_min_f32_e32 v8, 0x7f7fffff, v8
	v_min_f32_e32 v9, 0x7f7fffff, v9
	v_rcp_f32_e32 v10, v2
	v_rcp_f32_e32 v11, v3
	v_rcp_f32_e32 v12, v4
	v_rcp_f32_e32 v13, v5
	v_rcp_f32_e32 v14, v6
	v_rcp_f32_e32 v15, v7
	v_rcp_f32_e32 v16, v8
	v_rcp_f32_e32 v17, v9
	v_fma_f32 v18, -v2, v10, 1.0
	v_fma_f32 v19, -v3, v11, 1.0
	v_fma_f32 v20, -v4, v12, 1.0
	v_fma_f32 v21, -v5, v13, 1.0
	v_fma_f32 v22, -v6, v14, 1.0
	v_fma_f32 v23, -v7, v15, 1.0
	v_fma_f32 v24, -v8, v16, 1.0
	v_fma_f32 v25, -v9, v17, 1.0
	v_fmac_f32_e32 v10, v18, v10
	v_fmac_f32_e32 v11, v19, v11
	v_fmac_f32_e32 v12, v20, v12
	v_fmac_f32_e32 v13, v21, v13
	v_fmac_f32_e32 v14, v22, v14
	v_fmac_f32_e32 v15, v23, v15
	v_fmac_f32_e32 v16, v24, v16
	v_fmac_f32_e32 v17, v25, v17
	v_cvt_pk_bf16_f32 v10, v10, v10
	v_cvt_pk_bf16_f32 v11, v11, v11
	v_cvt_pk_bf16_f32 v12, v12, v12
	v_cvt_pk_bf16_f32 v13, v13, v13
	v_cvt_pk_bf16_f32 v14, v14, v14
	v_cvt_pk_bf16_f32 v15, v15, v15
	v_cvt_pk_bf16_f32 v16, v16, v16
	v_cvt_pk_bf16_f32 v17, v17, v17
	v_add_u32_e32 v26, 0x80000, v0
	global_store_short v26, v10, s[70:71]
	global_store_short v26, v11, s[70:71] offset:64
	v_add_u32_e32 v26, 0x82000, v0
	global_store_short v26, v12, s[70:71]
	global_store_short v26, v13, s[70:71] offset:64
	v_add_u32_e32 v26, 0x84000, v0
	global_store_short v26, v14, s[70:71]
	global_store_short v26, v15, s[70:71] offset:64
	v_add_u32_e32 v26, 0x86000, v0
	global_store_short v26, v16, s[70:71]
	global_store_short v26, v17, s[70:71] offset:64
	v_mul_f32_e32 v2, 0xbfb8aa3b, v97
	v_mul_f32_e32 v3, 0xbfb8aa3b, v81
	v_mul_f32_e32 v4, 0xbfb8aa3b, v96
	v_mul_f32_e32 v5, 0xbfb8aa3b, v80
	v_mul_f32_e32 v6, 0xbfb8aa3b, v95
	v_mul_f32_e32 v7, 0xbfb8aa3b, v79
	v_mul_f32_e32 v8, 0xbfb8aa3b, v94
	v_mul_f32_e32 v9, 0xbfb8aa3b, v78
	v_exp_f32_e32 v2, v2
	v_exp_f32_e32 v3, v3
	v_exp_f32_e32 v4, v4
	v_exp_f32_e32 v5, v5
	v_exp_f32_e32 v6, v6
	v_exp_f32_e32 v7, v7
	v_exp_f32_e32 v8, v8
	v_exp_f32_e32 v9, v9
	v_add_f32_e32 v2, 1.0, v2
	v_add_f32_e32 v3, 1.0, v3
	v_add_f32_e32 v4, 1.0, v4
	v_add_f32_e32 v5, 1.0, v5
	v_add_f32_e32 v6, 1.0, v6
	v_add_f32_e32 v7, 1.0, v7
	v_add_f32_e32 v8, 1.0, v8
	v_add_f32_e32 v9, 1.0, v9
	v_min_f32_e32 v2, 0x7f7fffff, v2
	v_min_f32_e32 v3, 0x7f7fffff, v3
	v_min_f32_e32 v4, 0x7f7fffff, v4
	v_min_f32_e32 v5, 0x7f7fffff, v5
	v_min_f32_e32 v6, 0x7f7fffff, v6
	v_min_f32_e32 v7, 0x7f7fffff, v7
	v_min_f32_e32 v8, 0x7f7fffff, v8
	v_min_f32_e32 v9, 0x7f7fffff, v9
	v_rcp_f32_e32 v10, v2
	v_rcp_f32_e32 v11, v3
	v_rcp_f32_e32 v12, v4
	v_rcp_f32_e32 v13, v5
; DI float sigmoidf_(float v) { return 1.f / (1.f + __expf(-v)); }
; DI void phase_in(const Params& p, int L, char* smem) {
;     ...
;         EPI_BEGINM(acc, 4) p.gates[(size_t)row * 4096 + (col - 2752)] = f2bf(sigmoidf_(v)); EPI_END
	v_rcp_f32_e32 v14, v6
	v_rcp_f32_e32 v15, v7
	v_rcp_f32_e32 v16, v8
	v_rcp_f32_e32 v17, v9
	v_fma_f32 v18, -v2, v10, 1.0
	v_fma_f32 v19, -v3, v11, 1.0
	v_fma_f32 v20, -v4, v12, 1.0
	v_fma_f32 v21, -v5, v13, 1.0
	v_fma_f32 v22, -v6, v14, 1.0
	v_fma_f32 v23, -v7, v15, 1.0
	v_fma_f32 v24, -v8, v16, 1.0
	v_fma_f32 v25, -v9, v17, 1.0
	v_fmac_f32_e32 v10, v18, v10
	v_fmac_f32_e32 v11, v19, v11
	v_fmac_f32_e32 v12, v20, v12
	v_fmac_f32_e32 v13, v21, v13
	v_fmac_f32_e32 v14, v22, v14
	v_fmac_f32_e32 v15, v23, v15
	v_fmac_f32_e32 v16, v24, v16
	v_fmac_f32_e32 v17, v25, v17
	v_cvt_pk_bf16_f32 v10, v10, v10
	v_cvt_pk_bf16_f32 v11, v11, v11
	v_cvt_pk_bf16_f32 v12, v12, v12
	v_cvt_pk_bf16_f32 v13, v13, v13
	v_cvt_pk_bf16_f32 v14, v14, v14
	v_cvt_pk_bf16_f32 v15, v15, v15
	v_cvt_pk_bf16_f32 v16, v16, v16
	v_cvt_pk_bf16_f32 v17, v17, v17
	v_add_u32_e32 v26, 0x90000, v0
	global_store_short v26, v10, s[70:71]
	global_store_short v26, v11, s[70:71] offset:64
	v_add_u32_e32 v26, 0x92000, v0
	global_store_short v26, v12, s[70:71]
	global_store_short v26, v13, s[70:71] offset:64
	v_add_u32_e32 v26, 0x94000, v0
	global_store_short v26, v14, s[70:71]
	global_store_short v26, v15, s[70:71] offset:64
	v_add_u32_e32 v26, 0x96000, v0
	global_store_short v26, v16, s[70:71]
	global_store_short v26, v17, s[70:71] offset:64
	v_mul_f32_e32 v2, 0xbfb8aa3b, v93
	v_mul_f32_e32 v3, 0xbfb8aa3b, v77
	v_mul_f32_e32 v4, 0xbfb8aa3b, v92
	v_mul_f32_e32 v5, 0xbfb8aa3b, v76
	v_mul_f32_e32 v6, 0xbfb8aa3b, v91
	v_mul_f32_e32 v7, 0xbfb8aa3b, v75
	v_mul_f32_e32 v8, 0xbfb8aa3b, v90
	v_mul_f32_e32 v9, 0xbfb8aa3b, v74
	v_exp_f32_e32 v2, v2
	v_exp_f32_e32 v3, v3
	v_exp_f32_e32 v4, v4
	v_exp_f32_e32 v5, v5
	v_exp_f32_e32 v6, v6
	v_exp_f32_e32 v7, v7
	v_exp_f32_e32 v8, v8
	v_exp_f32_e32 v9, v9
	v_add_f32_e32 v2, 1.0, v2
	v_add_f32_e32 v3, 1.0, v3
	v_add_f32_e32 v4, 1.0, v4
	v_add_f32_e32 v5, 1.0, v5
	v_add_f32_e32 v6, 1.0, v6
	v_add_f32_e32 v7, 1.0, v7
	v_add_f32_e32 v8, 1.0, v8
	v_add_f32_e32 v9, 1.0, v9
	v_min_f32_e32 v2, 0x7f7fffff, v2
	v_min_f32_e32 v3, 0x7f7fffff, v3
	v_min_f32_e32 v4, 0x7f7fffff, v4
	v_min_f32_e32 v5, 0x7f7fffff, v5
	v_min_f32_e32 v6, 0x7f7fffff, v6
	v_min_f32_e32 v7, 0x7f7fffff, v7
	v_min_f32_e32 v8, 0x7f7fffff, v8
	v_min_f32_e32 v9, 0x7f7fffff, v9
	v_rcp_f32_e32 v10, v2
	v_rcp_f32_e32 v11, v3
	v_rcp_f32_e32 v12, v4
	v_rcp_f32_e32 v13, v5
	v_rcp_f32_e32 v14, v6
	v_rcp_f32_e32 v15, v7
	v_rcp_f32_e32 v16, v8
	v_rcp_f32_e32 v17, v9
	v_fma_f32 v18, -v2, v10, 1.0
	v_fma_f32 v19, -v3, v11, 1.0
	v_fma_f32 v20, -v4, v12, 1.0
	v_fma_f32 v21, -v5, v13, 1.0
	v_fma_f32 v22, -v6, v14, 1.0
	v_fma_f32 v23, -v7, v15, 1.0
	v_fma_f32 v24, -v8, v16, 1.0
	v_fma_f32 v25, -v9, v17, 1.0
	v_fmac_f32_e32 v10, v18, v10
	v_fmac_f32_e32 v11, v19, v11
	v_fmac_f32_e32 v12, v20, v12
	v_fmac_f32_e32 v13, v21, v13
	v_fmac_f32_e32 v14, v22, v14
	v_fmac_f32_e32 v15, v23, v15
	v_fmac_f32_e32 v16, v24, v16
	v_fmac_f32_e32 v17, v25, v17
	v_cvt_pk_bf16_f32 v10, v10, v10
	v_cvt_pk_bf16_f32 v11, v11, v11
	v_cvt_pk_bf16_f32 v12, v12, v12
	v_cvt_pk_bf16_f32 v13, v13, v13
	v_cvt_pk_bf16_f32 v14, v14, v14
	v_cvt_pk_bf16_f32 v15, v15, v15
	v_cvt_pk_bf16_f32 v16, v16, v16
	v_cvt_pk_bf16_f32 v17, v17, v17
	v_add_u32_e32 v26, 0xa0000, v0
	global_store_short v26, v10, s[70:71]
	global_store_short v26, v11, s[70:71] offset:64
	v_add_u32_e32 v26, 0xa2000, v0
	global_store_short v26, v12, s[70:71]
	global_store_short v26, v13, s[70:71] offset:64
	v_add_u32_e32 v26, 0xa4000, v0
	global_store_short v26, v14, s[70:71]
	global_store_short v26, v15, s[70:71] offset:64
	v_add_u32_e32 v26, 0xa6000, v0
	global_store_short v26, v16, s[70:71]
	global_store_short v26, v17, s[70:71] offset:64
	v_mul_f32_e32 v2, 0xbfb8aa3b, v89
	v_mul_f32_e32 v3, 0xbfb8aa3b, v73
	v_mul_f32_e32 v4, 0xbfb8aa3b, v88
	v_mul_f32_e32 v5, 0xbfb8aa3b, v72
	v_mul_f32_e32 v6, 0xbfb8aa3b, v87
	v_mul_f32_e32 v7, 0xbfb8aa3b, v71
	v_mul_f32_e32 v8, 0xbfb8aa3b, v86
	v_mul_f32_e32 v9, 0xbfb8aa3b, v70
	v_exp_f32_e32 v2, v2
	v_exp_f32_e32 v3, v3
	v_exp_f32_e32 v4, v4
	v_exp_f32_e32 v5, v5
	v_exp_f32_e32 v6, v6
	v_exp_f32_e32 v7, v7
	v_exp_f32_e32 v8, v8
	v_exp_f32_e32 v9, v9
	v_add_f32_e32 v2, 1.0, v2
	v_add_f32_e32 v3, 1.0, v3
	v_add_f32_e32 v4, 1.0, v4
	v_add_f32_e32 v5, 1.0, v5
	v_add_f32_e32 v6, 1.0, v6
	v_add_f32_e32 v7, 1.0, v7
	v_add_f32_e32 v8, 1.0, v8
	v_add_f32_e32 v9, 1.0, v9
	v_min_f32_e32 v2, 0x7f7fffff, v2
	v_min_f32_e32 v3, 0x7f7fffff, v3
	v_min_f32_e32 v4, 0x7f7fffff, v4
	v_min_f32_e32 v5, 0x7f7fffff, v5
	v_min_f32_e32 v6, 0x7f7fffff, v6
	v_min_f32_e32 v7, 0x7f7fffff, v7
	v_min_f32_e32 v8, 0x7f7fffff, v8
	v_min_f32_e32 v9, 0x7f7fffff, v9
	v_rcp_f32_e32 v10, v2
	v_rcp_f32_e32 v11, v3
	v_rcp_f32_e32 v12, v4
	v_rcp_f32_e32 v13, v5
	v_rcp_f32_e32 v14, v6
	v_rcp_f32_e32 v15, v7
	v_rcp_f32_e32 v16, v8
	v_rcp_f32_e32 v17, v9
	v_fma_f32 v18, -v2, v10, 1.0
	v_fma_f32 v19, -v3, v11, 1.0
	v_fma_f32 v20, -v4, v12, 1.0
	v_fma_f32 v21, -v5, v13, 1.0
	v_fma_f32 v22, -v6, v14, 1.0
	v_fma_f32 v23, -v7, v15, 1.0
	v_fma_f32 v24, -v8, v16, 1.0
	v_fma_f32 v25, -v9, v17, 1.0
	v_fmac_f32_e32 v10, v18, v10
	v_fmac_f32_e32 v11, v19, v11
	v_fmac_f32_e32 v12, v20, v12
	v_fmac_f32_e32 v13, v21, v13
	v_fmac_f32_e32 v14, v22, v14
	v_fmac_f32_e32 v15, v23, v15
	v_fmac_f32_e32 v16, v24, v16
	v_fmac_f32_e32 v17, v25, v17
	v_cvt_pk_bf16_f32 v10, v10, v10
	v_cvt_pk_bf16_f32 v11, v11, v11
	v_cvt_pk_bf16_f32 v12, v12, v12
	v_cvt_pk_bf16_f32 v13, v13, v13
	v_cvt_pk_bf16_f32 v14, v14, v14
	v_cvt_pk_bf16_f32 v15, v15, v15
	v_cvt_pk_bf16_f32 v16, v16, v16
	v_cvt_pk_bf16_f32 v17, v17, v17
	v_add_u32_e32 v26, 0xb0000, v0
	global_store_short v26, v10, s[70:71]
	global_store_short v26, v11, s[70:71] offset:64
; DI float sigmoidf_(float v) { return 1.f / (1.f + __expf(-v)); }
; DI void phase_in(const Params& p, int L, char* smem) {
;     ...
;         EPI_BEGINM(acc, 4) p.gates[(size_t)row * 4096 + (col - 2752)] = f2bf(sigmoidf_(v)); EPI_END
	v_add_u32_e32 v26, 0xb2000, v0
	global_store_short v26, v12, s[70:71]
	global_store_short v26, v13, s[70:71] offset:64
	v_add_u32_e32 v26, 0xb4000, v0
	global_store_short v26, v14, s[70:71]
	global_store_short v26, v15, s[70:71] offset:64
	v_add_u32_e32 v26, 0xb6000, v0
	global_store_short v26, v16, s[70:71]
	global_store_short v26, v17, s[70:71] offset:64
	v_mul_f32_e32 v2, 0xbfb8aa3b, v69
	v_mul_f32_e32 v3, 0xbfb8aa3b, v53
	v_mul_f32_e32 v4, 0xbfb8aa3b, v68
	v_mul_f32_e32 v5, 0xbfb8aa3b, v52
	v_mul_f32_e32 v6, 0xbfb8aa3b, v67
	v_mul_f32_e32 v7, 0xbfb8aa3b, v51
	v_mul_f32_e32 v8, 0xbfb8aa3b, v66
	v_mul_f32_e32 v9, 0xbfb8aa3b, v50
	v_exp_f32_e32 v2, v2
	v_exp_f32_e32 v3, v3
	v_exp_f32_e32 v4, v4
	v_exp_f32_e32 v5, v5
	v_exp_f32_e32 v6, v6
	v_exp_f32_e32 v7, v7
	v_exp_f32_e32 v8, v8
	v_exp_f32_e32 v9, v9
	v_add_f32_e32 v2, 1.0, v2
	v_add_f32_e32 v3, 1.0, v3
	v_add_f32_e32 v4, 1.0, v4
	v_add_f32_e32 v5, 1.0, v5
	v_add_f32_e32 v6, 1.0, v6
	v_add_f32_e32 v7, 1.0, v7
	v_add_f32_e32 v8, 1.0, v8
	v_add_f32_e32 v9, 1.0, v9
	v_min_f32_e32 v2, 0x7f7fffff, v2
	v_min_f32_e32 v3, 0x7f7fffff, v3
	v_min_f32_e32 v4, 0x7f7fffff, v4
	v_min_f32_e32 v5, 0x7f7fffff, v5
	v_min_f32_e32 v6, 0x7f7fffff, v6
	v_min_f32_e32 v7, 0x7f7fffff, v7
	v_min_f32_e32 v8, 0x7f7fffff, v8
	v_min_f32_e32 v9, 0x7f7fffff, v9
	v_rcp_f32_e32 v10, v2
	v_rcp_f32_e32 v11, v3
	v_rcp_f32_e32 v12, v4
	v_rcp_f32_e32 v13, v5
	v_rcp_f32_e32 v14, v6
	v_rcp_f32_e32 v15, v7
	v_rcp_f32_e32 v16, v8
	v_rcp_f32_e32 v17, v9
	v_fma_f32 v18, -v2, v10, 1.0
	v_fma_f32 v19, -v3, v11, 1.0
	v_fma_f32 v20, -v4, v12, 1.0
	v_fma_f32 v21, -v5, v13, 1.0
	v_fma_f32 v22, -v6, v14, 1.0
	v_fma_f32 v23, -v7, v15, 1.0
	v_fma_f32 v24, -v8, v16, 1.0
	v_fma_f32 v25, -v9, v17, 1.0
	v_fmac_f32_e32 v10, v18, v10
	v_fmac_f32_e32 v11, v19, v11
	v_fmac_f32_e32 v12, v20, v12
	v_fmac_f32_e32 v13, v21, v13
	v_fmac_f32_e32 v14, v22, v14
	v_fmac_f32_e32 v15, v23, v15
	v_fmac_f32_e32 v16, v24, v16
	v_fmac_f32_e32 v17, v25, v17
	v_cvt_pk_bf16_f32 v10, v10, v10
	v_cvt_pk_bf16_f32 v11, v11, v11
	v_cvt_pk_bf16_f32 v12, v12, v12
	v_cvt_pk_bf16_f32 v13, v13, v13
	v_cvt_pk_bf16_f32 v14, v14, v14
	v_cvt_pk_bf16_f32 v15, v15, v15
	v_cvt_pk_bf16_f32 v16, v16, v16
	v_cvt_pk_bf16_f32 v17, v17, v17
	v_add_u32_e32 v26, 0xc0000, v0
	global_store_short v26, v10, s[70:71]
	global_store_short v26, v11, s[70:71] offset:64
	v_add_u32_e32 v26, 0xc2000, v0
	global_store_short v26, v12, s[70:71]
	global_store_short v26, v13, s[70:71] offset:64
	v_add_u32_e32 v26, 0xc4000, v0
	global_store_short v26, v14, s[70:71]
	global_store_short v26, v15, s[70:71] offset:64
	v_add_u32_e32 v26, 0xc6000, v0
	global_store_short v26, v16, s[70:71]
	global_store_short v26, v17, s[70:71] offset:64
	v_mul_f32_e32 v2, 0xbfb8aa3b, v65
	v_mul_f32_e32 v3, 0xbfb8aa3b, v49
	v_mul_f32_e32 v4, 0xbfb8aa3b, v64
	v_mul_f32_e32 v5, 0xbfb8aa3b, v48
	v_mul_f32_e32 v6, 0xbfb8aa3b, v63
	v_mul_f32_e32 v7, 0xbfb8aa3b, v47
	v_mul_f32_e32 v8, 0xbfb8aa3b, v62
	v_mul_f32_e32 v9, 0xbfb8aa3b, v46
	v_exp_f32_e32 v2, v2
	v_exp_f32_e32 v3, v3
	v_exp_f32_e32 v4, v4
	v_exp_f32_e32 v5, v5
	v_exp_f32_e32 v6, v6
	v_exp_f32_e32 v7, v7
	v_exp_f32_e32 v8, v8
	v_exp_f32_e32 v9, v9
	v_add_f32_e32 v2, 1.0, v2
	v_add_f32_e32 v3, 1.0, v3
	v_add_f32_e32 v4, 1.0, v4
	v_add_f32_e32 v5, 1.0, v5
	v_add_f32_e32 v6, 1.0, v6
	v_add_f32_e32 v7, 1.0, v7
	v_add_f32_e32 v8, 1.0, v8
	v_add_f32_e32 v9, 1.0, v9
	v_min_f32_e32 v2, 0x7f7fffff, v2
	v_min_f32_e32 v3, 0x7f7fffff, v3
	v_min_f32_e32 v4, 0x7f7fffff, v4
	v_min_f32_e32 v5, 0x7f7fffff, v5
	v_min_f32_e32 v6, 0x7f7fffff, v6
	v_min_f32_e32 v7, 0x7f7fffff, v7
	v_min_f32_e32 v8, 0x7f7fffff, v8
	v_min_f32_e32 v9, 0x7f7fffff, v9
	v_rcp_f32_e32 v10, v2
	v_rcp_f32_e32 v11, v3
	v_rcp_f32_e32 v12, v4
	v_rcp_f32_e32 v13, v5
	v_rcp_f32_e32 v14, v6
	v_rcp_f32_e32 v15, v7
	v_rcp_f32_e32 v16, v8
	v_rcp_f32_e32 v17, v9
	v_fma_f32 v18, -v2, v10, 1.0
	v_fma_f32 v19, -v3, v11, 1.0
	v_fma_f32 v20, -v4, v12, 1.0
	v_fma_f32 v21, -v5, v13, 1.0
	v_fma_f32 v22, -v6, v14, 1.0
	v_fma_f32 v23, -v7, v15, 1.0
	v_fma_f32 v24, -v8, v16, 1.0
	v_fma_f32 v25, -v9, v17, 1.0
	v_fmac_f32_e32 v10, v18, v10
	v_fmac_f32_e32 v11, v19, v11
	v_fmac_f32_e32 v12, v20, v12
	v_fmac_f32_e32 v13, v21, v13
	v_fmac_f32_e32 v14, v22, v14
	v_fmac_f32_e32 v15, v23, v15
	v_fmac_f32_e32 v16, v24, v16
	v_fmac_f32_e32 v17, v25, v17
	v_cvt_pk_bf16_f32 v10, v10, v10
	v_cvt_pk_bf16_f32 v11, v11, v11
	v_cvt_pk_bf16_f32 v12, v12, v12
	v_cvt_pk_bf16_f32 v13, v13, v13
	v_cvt_pk_bf16_f32 v14, v14, v14
	v_cvt_pk_bf16_f32 v15, v15, v15
	v_cvt_pk_bf16_f32 v16, v16, v16
	v_cvt_pk_bf16_f32 v17, v17, v17
	v_add_u32_e32 v26, 0xd0000, v0
	global_store_short v26, v10, s[70:71]
	global_store_short v26, v11, s[70:71] offset:64
	v_add_u32_e32 v26, 0xd2000, v0
	global_store_short v26, v12, s[70:71]
	global_store_short v26, v13, s[70:71] offset:64
	v_add_u32_e32 v26, 0xd4000, v0
	global_store_short v26, v14, s[70:71]
; DI float sigmoidf_(float v) { return 1.f / (1.f + __expf(-v)); }
; DI void phase_in(const Params& p, int L, char* smem) {
;     ...
;     if (cb >= 43) {
;       if (cb < 107) {
;         EPI_BEGINM(acc, 4) p.gates[(size_t)row * 4096 + (col - 2752)] = f2bf(sigmoidf_(v)); EPI_END
;       }
	global_store_short v26, v15, s[70:71] offset:64
	v_add_u32_e32 v26, 0xd6000, v0
	global_store_short v26, v16, s[70:71]
	global_store_short v26, v17, s[70:71] offset:64
	v_mul_f32_e32 v2, 0xbfb8aa3b, v61
	v_mul_f32_e32 v3, 0xbfb8aa3b, v45
	v_mul_f32_e32 v4, 0xbfb8aa3b, v60
	v_mul_f32_e32 v5, 0xbfb8aa3b, v44
	v_mul_f32_e32 v6, 0xbfb8aa3b, v59
	v_mul_f32_e32 v7, 0xbfb8aa3b, v43
	v_mul_f32_e32 v8, 0xbfb8aa3b, v58
	v_mul_f32_e32 v9, 0xbfb8aa3b, v42
	v_exp_f32_e32 v2, v2
	v_exp_f32_e32 v3, v3
	v_exp_f32_e32 v4, v4
	v_exp_f32_e32 v5, v5
	v_exp_f32_e32 v6, v6
	v_exp_f32_e32 v7, v7
	v_exp_f32_e32 v8, v8
	v_exp_f32_e32 v9, v9
	v_add_f32_e32 v2, 1.0, v2
	v_add_f32_e32 v3, 1.0, v3
	v_add_f32_e32 v4, 1.0, v4
	v_add_f32_e32 v5, 1.0, v5
	v_add_f32_e32 v6, 1.0, v6
	v_add_f32_e32 v7, 1.0, v7
	v_add_f32_e32 v8, 1.0, v8
	v_add_f32_e32 v9, 1.0, v9
	v_min_f32_e32 v2, 0x7f7fffff, v2
	v_min_f32_e32 v3, 0x7f7fffff, v3
	v_min_f32_e32 v4, 0x7f7fffff, v4
	v_min_f32_e32 v5, 0x7f7fffff, v5
	v_min_f32_e32 v6, 0x7f7fffff, v6
	v_min_f32_e32 v7, 0x7f7fffff, v7
	v_min_f32_e32 v8, 0x7f7fffff, v8
	v_min_f32_e32 v9, 0x7f7fffff, v9
	v_rcp_f32_e32 v10, v2
	v_rcp_f32_e32 v11, v3
	v_rcp_f32_e32 v12, v4
	v_rcp_f32_e32 v13, v5
	v_rcp_f32_e32 v14, v6
	v_rcp_f32_e32 v15, v7
	v_rcp_f32_e32 v16, v8
	v_rcp_f32_e32 v17, v9
	v_fma_f32 v18, -v2, v10, 1.0
	v_fma_f32 v19, -v3, v11, 1.0
	v_fma_f32 v20, -v4, v12, 1.0
	v_fma_f32 v21, -v5, v13, 1.0
	v_fma_f32 v22, -v6, v14, 1.0
	v_fma_f32 v23, -v7, v15, 1.0
	v_fma_f32 v24, -v8, v16, 1.0
	v_fma_f32 v25, -v9, v17, 1.0
	v_fmac_f32_e32 v10, v18, v10
	v_fmac_f32_e32 v11, v19, v11
	v_fmac_f32_e32 v12, v20, v12
	v_fmac_f32_e32 v13, v21, v13
	v_fmac_f32_e32 v14, v22, v14
	v_fmac_f32_e32 v15, v23, v15
	v_fmac_f32_e32 v16, v24, v16
	v_fmac_f32_e32 v17, v25, v17
	v_cvt_pk_bf16_f32 v10, v10, v10
	v_cvt_pk_bf16_f32 v11, v11, v11
	v_cvt_pk_bf16_f32 v12, v12, v12
	v_cvt_pk_bf16_f32 v13, v13, v13
	v_cvt_pk_bf16_f32 v14, v14, v14
	v_cvt_pk_bf16_f32 v15, v15, v15
	v_cvt_pk_bf16_f32 v16, v16, v16
	v_cvt_pk_bf16_f32 v17, v17, v17
	v_add_u32_e32 v26, 0xe0000, v0
	global_store_short v26, v10, s[70:71]
	global_store_short v26, v11, s[70:71] offset:64
	v_add_u32_e32 v26, 0xe2000, v0
	global_store_short v26, v12, s[70:71]
	global_store_short v26, v13, s[70:71] offset:64
	v_add_u32_e32 v26, 0xe4000, v0
	global_store_short v26, v14, s[70:71]
	global_store_short v26, v15, s[70:71] offset:64
	v_add_u32_e32 v26, 0xe6000, v0
	global_store_short v26, v16, s[70:71]
	global_store_short v26, v17, s[70:71] offset:64
	v_mul_f32_e32 v2, 0xbfb8aa3b, v57
	v_mul_f32_e32 v3, 0xbfb8aa3b, v41
	v_mul_f32_e32 v4, 0xbfb8aa3b, v56
	v_mul_f32_e32 v5, 0xbfb8aa3b, v40
	v_mul_f32_e32 v6, 0xbfb8aa3b, v55
	v_mul_f32_e32 v7, 0xbfb8aa3b, v39
	v_mul_f32_e32 v8, 0xbfb8aa3b, v54
	v_mul_f32_e32 v9, 0xbfb8aa3b, v38
	v_exp_f32_e32 v2, v2
	v_exp_f32_e32 v3, v3
	v_exp_f32_e32 v4, v4
	v_exp_f32_e32 v5, v5
	v_exp_f32_e32 v6, v6
	v_exp_f32_e32 v7, v7
	v_exp_f32_e32 v8, v8
	v_exp_f32_e32 v9, v9
	v_add_f32_e32 v2, 1.0, v2
	v_add_f32_e32 v3, 1.0, v3
	v_add_f32_e32 v4, 1.0, v4
	v_add_f32_e32 v5, 1.0, v5
	v_add_f32_e32 v6, 1.0, v6
	v_add_f32_e32 v7, 1.0, v7
	v_add_f32_e32 v8, 1.0, v8
	v_add_f32_e32 v9, 1.0, v9
	v_min_f32_e32 v2, 0x7f7fffff, v2
	v_min_f32_e32 v3, 0x7f7fffff, v3
	v_min_f32_e32 v4, 0x7f7fffff, v4
	v_min_f32_e32 v5, 0x7f7fffff, v5
	v_min_f32_e32 v6, 0x7f7fffff, v6
	v_min_f32_e32 v7, 0x7f7fffff, v7
	v_min_f32_e32 v8, 0x7f7fffff, v8
	v_min_f32_e32 v9, 0x7f7fffff, v9
	v_rcp_f32_e32 v10, v2
	v_rcp_f32_e32 v11, v3
	v_rcp_f32_e32 v12, v4
	v_rcp_f32_e32 v13, v5
	v_rcp_f32_e32 v14, v6
	v_rcp_f32_e32 v15, v7
	v_rcp_f32_e32 v16, v8
	v_rcp_f32_e32 v17, v9
	v_fma_f32 v18, -v2, v10, 1.0
	v_fma_f32 v19, -v3, v11, 1.0
	v_fma_f32 v20, -v4, v12, 1.0
	v_fma_f32 v21, -v5, v13, 1.0
	v_fma_f32 v22, -v6, v14, 1.0
	v_fma_f32 v23, -v7, v15, 1.0
	v_fma_f32 v24, -v8, v16, 1.0
	v_fma_f32 v25, -v9, v17, 1.0
	v_fmac_f32_e32 v10, v18, v10
	v_fmac_f32_e32 v11, v19, v11
	v_fmac_f32_e32 v12, v20, v12
	v_fmac_f32_e32 v13, v21, v13
	v_fmac_f32_e32 v14, v22, v14
	v_fmac_f32_e32 v15, v23, v15
	v_fmac_f32_e32 v16, v24, v16
	v_fmac_f32_e32 v17, v25, v17
	v_cvt_pk_bf16_f32 v10, v10, v10
	v_cvt_pk_bf16_f32 v11, v11, v11
	v_cvt_pk_bf16_f32 v12, v12, v12
	v_cvt_pk_bf16_f32 v13, v13, v13
	v_cvt_pk_bf16_f32 v14, v14, v14
	v_cvt_pk_bf16_f32 v15, v15, v15
	v_cvt_pk_bf16_f32 v16, v16, v16
	v_cvt_pk_bf16_f32 v17, v17, v17
	v_add_u32_e32 v26, 0xf0000, v0
	global_store_short v26, v10, s[70:71]
	global_store_short v26, v11, s[70:71] offset:64
	v_add_u32_e32 v26, 0xf2000, v0
	global_store_short v26, v12, s[70:71]
	global_store_short v26, v13, s[70:71] offset:64
	v_add_u32_e32 v26, 0xf4000, v0
	global_store_short v26, v14, s[70:71]
	global_store_short v26, v15, s[70:71] offset:64
	v_add_u32_e32 v26, 0xf6000, v0
	global_store_short v26, v16, s[70:71]
	global_store_short v26, v17, s[70:71] offset:64
	s_branch .LBB0_778
